# attention stage: waves 4-7 start ~1000 cycles late (s_sleep 16) so SIMD partner waves alternate MFMA and VALU stages
# speedup vs baseline: 1.0009x; 1.0009x over previous
; #define LAS __attribute__((address_space(3)))
; __device__ __forceinline__ void p2_block(LAS unsigned char* lds, const bf16_t* __restrict__ PROJ, bf16_t* __restrict__ ATT, bf16_t* __restrict__ SGU, const float* __restrict__ qn, const float* __restrict__ kn, ...
;     ...
;     const int b = item >> 6, n = (item >> 2) & 15, kvh = item & 3;
;     const int lane = tid & 63, w = __builtin_amdgcn_readfirstlane(tid >> 6), fr = lane & 15, fq = lane >> 4;
;     LAS unsigned char* KS = lds; LAS unsigned char* VT = lds + KS_BYTES;
;     const int g = w >> 1, rbase = (w & 1) * 64, hq = kvh * 4 + g;
;     const int kk = tid >> 1, h = tid & 1, s = n * 128 - 128 + kk, sc = s < 0 ? 0 : s;
;     const bf16_t* rowp = PROJ + (size_t)(b * pg8::SEQ + sc) * pg8::IN_W;
;     const bf16_t* kp = rowp + pg8::C_K + kvh * 64 + 16 * h;
;     const u32x4 ka = *(const u32x4*)kp, kb = *(const u32x4*)(kp + 8), kc = *(const u32x4*)(kp + 32), kd = *(const u32x4*)(kp + 40);
;     const bf16_t* vp = rowp + pg8::C_V + kvh * 64 + 32 * h;
;     u32x4 vv[4];
; #pragma unroll
;     for (int c4 = 0; c4 < 4; ++c4) vv[c4] = *(const u32x4*)(vp + 8 * c4);
;     const int sp_ = tid >> 2, q4 = tid & 3;
;     u32x4 sv[2][4];
;     const bf16_t* svsrc = PROJ + ((size_t)b * pg8::SEQ + n * 128 + sp_) * pg8::IN_W + pg8::C_VS + (2 * kvh) * 128 + 32 * q4;
; #pragma unroll
;     for (int c4 = 0; c4 < 4; ++c4) sv[0][c4] = *(const u32x4*)(svsrc + 8 * c4);
;     u32x4 qa[4], qb[4];
; #pragma unroll
;     for (int c = 0; c < 2; ++c) { const bf16_t* qp = PROJ + ((size_t)b * pg8::SEQ + n * 128 + rbase + 16 * c + fr) * pg8::IN_W + hq * 64 + 8 * fq; qa[c] = *(const u32x4*)qp; qb[c] = *(const u32x4*)(qp + 32); }
.LBB0_330:
	s_bfe_u32 s27, s2, 0x40002
	v_mov_b32_e32 v160, v204
	s_lshl_b32 s17, s27, 7
	s_add_i32 s4, s17, 0xffffff80
	v_ashrrev_i32_e32 v167, 1, v160
	v_add_u32_e32 v22, s4, v167
	s_ashr_i32 s6, s2, 6
	v_max_i32_e32 v66, 0, v22
	s_and_b32 s73, s2, 3
	v_lshl_add_u32 v0, s6, 11, v66
	s_waitcnt lgkmcnt(0)
	v_mov_b64_e32 v[2:3], s[10:11]
	v_and_b32_e32 v166, 1, v160
	v_mad_i64_i32 v[4:5], s[24:25], v0, s83, v[2:3]
	s_lshl_b32 s4, s73, 7
	v_lshl_add_u64 v[4:5], v[4:5], 0, s[4:5]
	v_lshlrev_b32_e32 v0, 5, v166
	v_lshl_add_u64 v[6:7], v[4:5], 0, v[0:1]
	global_load_dwordx4 v[50:53], v[6:7], off offset:2048
	global_load_dwordx4 v[58:61], v[6:7], off offset:2064
	global_load_dwordx4 v[54:57], v[6:7], off offset:2112
	global_load_dwordx4 v[62:65], v[6:7], off offset:2128
	v_readfirstlane_b32 s16, v160
	s_ashr_i32 s77, s16, 7
	s_lshl_b32 s7, s73, 2
	s_add_i32 s42, s77, s7
	s_ashr_i32 s7, s6, 31
	v_lshlrev_b32_e32 v74, 6, v166
	v_mov_b32_e32 v75, v1
	v_ashrrev_i32_e32 v136, 2, v160
	s_lshl_b64 s[48:49], s[6:7], 11
	v_lshl_add_u64 v[4:5], v[4:5], 0, v[74:75]
	s_or_b32 s24, s48, s17
	s_mov_b32 s25, s49
	v_ashrrev_i32_e32 v137, 31, v136
	s_waitcnt lgkmcnt(0)
	v_mov_b64_e32 v[144:145], v[4:5]
	s_nop 0
	s_nop 0
	s_nop 0
	v_lshl_add_u64 v[4:5], s[24:25], 0, v[136:137]
	v_mad_u64_u32 v[2:3], s[6:7], v4, s83, v[2:3]
	v_lshlrev_b32_e32 v4, 5, v160
	v_mad_i32_i24 v3, v5, s83, v3
	s_lshl_b32 s4, s73, 9
	v_and_b32_e32 v165, 0x60, v4
	v_lshl_add_u64 v[2:3], v[2:3], 0, s[4:5]
	v_lshlrev_b32_e32 v4, 1, v165
	v_mov_b32_e32 v5, v1
	v_lshl_add_u64 v[2:3], v[2:3], 0, v[4:5]
	s_mov_b64 s[6:7], 0x1400
	v_lshl_add_u64 v[138:139], v[2:3], 0, s[6:7]
	s_lshl_b32 s6, s42, 6
	s_ashr_i32 s7, s6, 31
	s_and_b32 s26, s16, 64
	s_lshl_b64 s[6:7], s[6:7], 1
	v_bfe_u32 v162, v160, 4, 2
	s_add_u32 s28, s10, s6
	s_movk_i32 s4, 0x1000
	v_and_b32_e32 v137, 15, v160
	s_addc_u32 s29, s11, s7
	v_lshlrev_b32_e32 v132, 4, v162
	v_mov_b32_e32 v133, v1
	v_and_b32_e32 v68, 64, v211
	v_add_co_u32_e32 v2, vcc, s4, v2
	v_or_b32_e32 v161, s26, v137
	v_lshl_add_u64 v[134:135], s[28:29], 0, v[132:133]
	v_xor_b32_e32 v67, 1, v211
	v_add_u32_e32 v133, 64, v68
	v_addc_co_u32_e32 v3, vcc, 0, v3, vcc
	v_or_b32_e32 v163, s24, v161
	v_cmp_lt_i32_e64 s[40:41], v67, v133
	v_cmp_gt_i32_e32 vcc, 0, v22
	v_mad_u64_u32 v[22:23], s[28:29], v163, s83, v[134:135]
	v_cndmask_b32_e64 v67, v211, v67, s[40:41]
	v_mad_i32_i24 v23, s49, v212, v23
	v_lshlrev_b32_e32 v164, 2, v67
	v_lshlrev_b32_e32 v66, 5, v66
	v_mov_b32_e32 v67, v1
	v_readlane_b32 s44, v250, 36
	v_readlane_b32 s46, v250, 38
	s_nop 0
	s_nop 0
	s_nop 0
	s_nop 0
	s_nop 0
	v_or_b32_e32 v22, 16, v163
	v_lshlrev_b64 v[66:67], 2, v[66:67]
	v_readlane_b32 s45, v250, 37
	v_readlane_b32 s47, v250, 39
	v_mad_u64_u32 v[26:27], s[28:29], v22, s83, v[134:135]
	v_lshl_add_u64 v[68:69], s[44:45], 0, v[66:67]
	v_lshl_add_u64 v[66:67], s[46:47], 0, v[66:67]
	v_mad_i32_i24 v27, s49, v212, v27
	v_lshl_add_u64 v[86:87], v[68:69], 0, v[74:75]
	v_lshl_add_u64 v[126:127], v[66:67], 0, v[74:75]
	s_nop 0
	s_nop 0
	global_load_dwordx4 v[66:69], v74, s[0:1] offset:48
	global_load_dwordx4 v[78:81], v74, s[0:1] offset:32
	global_load_dwordx4 v[94:97], v74, s[0:1] offset:16
	global_load_dwordx4 v[106:109], v74, s[0:1]
	global_load_dwordx4 v[70:73], v74, s[0:1] offset:176
	global_load_dwordx4 v[82:85], v74, s[0:1] offset:160
	global_load_dwordx4 v[98:101], v74, s[0:1] offset:144
	global_load_dwordx4 v[110:113], v74, s[0:1] offset:128
	s_nop 0
	global_load_dwordx4 v[74:77], v[86:87], off offset:48
	global_load_dwordx4 v[90:93], v[86:87], off offset:32
	global_load_dwordx4 v[102:105], v[86:87], off offset:16
	global_load_dwordx4 v[114:117], v[86:87], off
	s_nop 0
	global_load_dwordx4 v[86:89], v[126:127], off offset:48
	global_load_dwordx4 v[118:121], v[126:127], off offset:32
	global_load_dwordx4 v[122:125], v[126:127], off offset:16
	s_nop 0
	global_load_dwordx4 v[126:129], v[126:127], off
	v_cndmask_b32_e64 v180, 1.0, 0, vcc
	s_lshl_b32 s4, s73, 10
	global_load_dwordx4 v[46:49], v[2:3], off offset:1024
	global_load_dwordx4 v[34:37], v[138:139], off offset:48
	global_load_dwordx4 v[38:41], v[138:139], off offset:32
	global_load_dwordx4 v[42:45], v[138:139], off offset:16
	global_load_dwordx4 v[18:21], v[144:145], off offset:2560
	global_load_dwordx4 v[14:17], v[144:145], off offset:2576
	global_load_dwordx4 v[10:13], v[144:145], off offset:2592
	global_load_dwordx4 v[6:9], v[144:145], off offset:2608
	s_waitcnt vmcnt(8)
; __device__ __forceinline__ void unpack8(const u32x4 w, float* f) { f[0] = bf_lo(w.x); f[1] = bf_hi(w.x); f[2] = bf_lo(w.y); f[3] = bf_hi(w.y); f[4] = bf_lo(w.z); f[5] = bf_hi(w.z); f[6] = bf_lo(w.w); f[7] = bf_hi(w.w); }
; __device__ __forceinline__ void p2_block(LAS unsigned char* lds, const bf16_t* __restrict__ PROJ, bf16_t* __restrict__ ATT, bf16_t* __restrict__ SGU, const float* __restrict__ qn, const float* __restrict__ kn, ...
;     ...
;         const float valid = s < 0 ? 0.f : 1.f;
;         float x1[16], x2[16]; unpack8(ka, x1); unpack8(kb, x1 + 8); unpack8(kc, x2); unpack8(kd, x2 + 8);
;         float ss = 0.f;
; #pragma unroll
;         for (int j = 0; j < 16; ++j) ss += x1[j] * x1[j] + x2[j] * x2[j];
;         ss += __shfl_xor(ss, 1);
;         const float rinv = rsqrtf(ss * (1.0f / 64.0f) + pg8::EPS) * valid;
;         const float* cp = COS + sc * 32 + 16 * h; const float* sp = SIN + sc * 32 + 16 * h;
;         float o1[16], o2[16];
; #pragma unroll
;         for (int j = 0; j < 16; ++j) { const float a1 = x1[j] * rinv * kn[16 * h + j], a2 = x2[j] * rinv * kn[32 + 16 * h + j], c = cp[j], sn = sp[j]; o1[j] = a1 * c - a2 * sn; o2[j] = a2 * c + a1 * sn; }
	v_lshlrev_b32_e32 v226, 16, v51
	v_lshlrev_b32_e32 v142, 16, v61
	v_and_b32_e32 v140, 0xffff0000, v61
	v_lshlrev_b32_e32 v143, 16, v65
	v_and_b32_e32 v141, 0xffff0000, v65
	v_mov_b32_e32 v150, v141
	v_mov_b32_e32 v151, v143
	v_mov_b32_e32 v148, v140
	v_mov_b32_e32 v149, v142
	v_pk_mul_f32 v[150:151], v[150:151], v[150:151]
	v_and_b32_e32 v61, 0xffff0000, v64
	v_pk_fma_f32 v[182:183], v[148:149], v[148:149], v[150:151]
	v_lshlrev_b32_e32 v149, 16, v64
	v_lshlrev_b32_e32 v148, 16, v60
	v_and_b32_e32 v60, 0xffff0000, v60
	v_mov_b32_e32 v154, v61
	v_mov_b32_e32 v155, v149
	v_mov_b32_e32 v64, v60
	v_mov_b32_e32 v65, v148
	v_pk_mul_f32 v[154:155], v[154:155], v[154:155]
	v_and_b32_e32 v201, 0xffff0000, v57
	v_pk_fma_f32 v[184:185], v[64:65], v[64:65], v[154:155]
	v_lshlrev_b32_e32 v155, 16, v63
	v_and_b32_e32 v65, 0xffff0000, v63
	v_lshlrev_b32_e32 v154, 16, v59
	v_and_b32_e32 v64, 0xffff0000, v59
	v_mov_b32_e32 v188, v65
	v_mov_b32_e32 v189, v155
	v_mov_b32_e32 v186, v64
	v_mov_b32_e32 v187, v154
	v_pk_mul_f32 v[188:189], v[188:189], v[188:189]
	v_and_b32_e32 v59, 0xffff0000, v62
	v_pk_fma_f32 v[186:187], v[186:187], v[186:187], v[188:189]
	v_lshlrev_b32_e32 v189, 16, v62
	v_lshlrev_b32_e32 v188, 16, v58
	v_and_b32_e32 v58, 0xffff0000, v58
	v_mov_b32_e32 v194, v59
	v_mov_b32_e32 v195, v189
	v_mov_b32_e32 v62, v58
	v_mov_b32_e32 v63, v188
	v_pk_mul_f32 v[194:195], v[194:195], v[194:195]
	v_and_b32_e32 v234, 0xffff0000, v51
	v_pk_fma_f32 v[62:63], v[62:63], v[62:63], v[194:195]
	v_lshlrev_b32_e32 v195, 16, v57
	v_lshlrev_b32_e32 v239, 16, v54
	v_lshlrev_b32_e32 v238, 16, v50
	v_and_b32_e32 v51, 0xffff0000, v54
	v_and_b32_e32 v50, 0xffff0000, v50
	v_lshlrev_b32_e32 v194, 16, v53
	v_and_b32_e32 v200, 0xffff0000, v53
	v_mov_b32_e32 v218, v201
	v_mov_b32_e32 v219, v195
	v_lshlrev_b32_e32 v227, 16, v55
	v_and_b32_e32 v235, 0xffff0000, v55
	v_pk_mul_f32 v[240:241], v[238:239], v[238:239]
	v_pk_mul_f32 v[54:55], v[50:51], v[50:51]
	v_mov_b32_e32 v202, v200
	v_mov_b32_e32 v203, v194
	v_pk_mul_f32 v[218:219], v[218:219], v[218:219]
	v_pk_mul_f32 v[228:229], v[226:227], v[226:227]
	v_add_f32_e32 v54, v54, v55
	v_add_f32_e32 v55, v240, v241
	v_pk_fma_f32 v[202:203], v[202:203], v[202:203], v[218:219]
	v_lshlrev_b32_e32 v219, 16, v56
	v_lshlrev_b32_e32 v218, 16, v52
	v_pk_mul_f32 v[236:237], v[234:235], v[234:235]
	v_add_f32_e32 v54, v55, v54
	v_add_f32_e32 v55, v228, v229
	v_mov_b32_e32 v150, v66
	v_pk_mul_f32 v[220:221], v[218:219], v[218:219]
	v_and_b32_e32 v53, 0xffff0000, v56
	v_and_b32_e32 v52, 0xffff0000, v52
	v_add_f32_e32 v66, v236, v237
	v_add_f32_e32 v54, v55, v54
	v_pk_mul_f32 v[56:57], v[52:53], v[52:53]
	v_add_f32_e32 v54, v66, v54
	v_add_f32_e32 v55, v220, v221
	v_add_f32_e32 v54, v55, v54
	v_add_f32_e32 v55, v56, v57
	v_add_f32_e32 v54, v55, v54
	v_add_f32_e32 v54, v203, v54
	v_add_f32_e32 v54, v202, v54
	v_add_f32_e32 v54, v63, v54
	v_add_f32_e32 v54, v62, v54
	v_add_f32_e32 v54, v187, v54
	v_add_f32_e32 v54, v186, v54
	v_add_f32_e32 v54, v185, v54
	v_add_f32_e32 v54, v184, v54
	v_add_f32_e32 v54, v183, v54
	v_add_f32_e32 v54, v182, v54
	s_nop 1
	v_mov_b32_dpp v55, v54 quad_perm:[1,0,3,2] row_mask:0xf bank_mask:0xf
	v_mov_b32_e32 v242, v106
	v_mov_b32_e32 v243, v110
	v_mov_b32_e32 v244, v114
	v_mov_b32_e32 v245, v126
	s_waitcnt lgkmcnt(0)
	v_add_f32_e32 v54, v54, v55
	v_fmamk_f32 v54, v54, 0x3c800000, v209
	v_cmp_gt_f32_e64 s[40:41], s82, v54
	v_mul_f32_e32 v55, 0x4b800000, v54
	v_mov_b32_e32 v110, v107
	v_cndmask_b32_e64 v54, v54, v55, s[40:41]
	v_rsq_f32_e32 v54, v54
	v_mov_b32_e32 v230, v108
	v_mov_b32_e32 v231, v112
	v_mov_b32_e32 v232, v116
	v_mul_f32_e32 v55, 0x45800000, v54
	v_cndmask_b32_e64 v54, v54, v55, s[40:41]
	v_mul_f32_e32 v54, v180, v54
	v_pk_mul_f32 v[56:57], v[54:55], v[238:239] op_sel_hi:[0,1]
	v_pk_mul_f32 v[56:57], v[242:243], v[56:57]
	v_mov_b32_e32 v233, v128
	v_pk_mul_f32 v[62:63], v[244:245], v[56:57]
	v_mov_b32_e32 v144, v68
	v_sub_f32_e32 v55, v62, v63
	v_mov_b32_e32 v62, v126
	v_mov_b32_e32 v63, v114
	v_pk_mul_f32 v[50:51], v[54:55], v[50:51] op_sel_hi:[0,1]
	v_pk_mul_f32 v[56:57], v[62:63], v[56:57]
	v_pk_mul_f32 v[50:51], v[110:111], v[50:51]
	v_mov_b32_e32 v126, v115
	v_mov_b32_e32 v114, v127
	v_add_f32_e32 v62, v57, v56
	v_pk_mul_f32 v[56:57], v[126:127], v[50:51]
	v_pk_mul_f32 v[50:51], v[114:115], v[50:51]
	v_sub_f32_e32 v63, v56, v57
	v_add_f32_e32 v66, v51, v50
	v_pk_mul_f32 v[50:51], v[54:55], v[226:227] op_sel_hi:[0,1]
	v_pk_mul_f32 v[50:51], v[230:231], v[50:51]
	v_mov_b32_e32 v190, v78
	v_pk_mul_f32 v[56:57], v[232:233], v[50:51]
	v_mov_b32_e32 v112, v109
	v_sub_f32_e32 v68, v56, v57
	v_mov_b32_e32 v56, v128
	v_mov_b32_e32 v57, v116
	v_pk_mul_f32 v[50:51], v[56:57], v[50:51]
	v_mov_b32_e32 v128, v117
	v_add_f32_e32 v78, v51, v50
	v_pk_mul_f32 v[50:51], v[54:55], v[234:235] op_sel_hi:[0,1]
	v_pk_mul_f32 v[50:51], v[112:113], v[50:51]
	v_mov_b32_e32 v116, v129
	v_pk_mul_f32 v[56:57], v[128:129], v[50:51]
	v_pk_mul_f32 v[50:51], v[116:117], v[50:51]
	v_mov_b32_e32 v222, v94
	v_mov_b32_e32 v223, v98
	v_add_f32_e32 v94, v51, v50
	v_pk_mul_f32 v[50:51], v[54:55], v[218:219] op_sel_hi:[0,1]
	v_mov_b32_e32 v224, v102
	v_mov_b32_e32 v225, v122
	v_pk_mul_f32 v[50:51], v[50:51], v[222:223]
	v_mov_b32_e32 v156, v80
	v_sub_f32_e32 v80, v56, v57
	v_pk_mul_f32 v[56:57], v[50:51], v[224:225]
	v_mov_b32_e32 v196, v96
	v_sub_f32_e32 v96, v56, v57
	v_mov_b32_e32 v56, v122
	v_mov_b32_e32 v57, v102
	v_pk_mul_f32 v[50:51], v[50:51], v[56:57]
	v_mov_b32_e32 v98, v95
	v_add_f32_e32 v106, v51, v50
	v_pk_mul_f32 v[50:51], v[54:55], v[52:53] op_sel_hi:[0,1]
	v_pk_mul_f32 v[50:51], v[50:51], v[98:99]
	v_mov_b32_e32 v122, v103
; __device__ __forceinline__ unsigned cvt_pk_bf16(float lo, float hi) { unsigned r; asm volatile("v_cvt_pk_bf16_f32 %0, %1, %2" : "=v"(r) : "v"(lo), "v"(hi)); return r; }
; #define LAS __attribute__((address_space(3)))
; __device__ __forceinline__ void p2_block(LAS unsigned char* lds, const bf16_t* __restrict__ PROJ, bf16_t* __restrict__ ATT, bf16_t* __restrict__ SGU, const float* __restrict__ qn, const float* __restrict__ kn, ...
;     ...
;         for (int j = 0; j < 16; ++j) { const float a1 = x1[j] * rinv * kn[16 * h + j], a2 = x2[j] * rinv * kn[32 + 16 * h + j], c = cp[j], sn = sp[j]; o1[j] = a1 * c - a2 * sn; o2[j] = a2 * c + a1 * sn; }
;         LAS unsigned char* kdst = KS + kk * KS_STRIDE + 32 * h;
;         u32x4 w0, w1;
;         w0.x = cvt_pk_bf16(o1[0], o1[1]); w0.y = cvt_pk_bf16(o1[2], o1[3]); w0.z = cvt_pk_bf16(o1[4], o1[5]); w0.w = cvt_pk_bf16(o1[6], o1[7]);
;         w1.x = cvt_pk_bf16(o1[8], o1[9]); w1.y = cvt_pk_bf16(o1[10], o1[11]); w1.z = cvt_pk_bf16(o1[12], o1[13]); w1.w = cvt_pk_bf16(o1[14], o1[15]);
;         *(LAS u32x4*)kdst = w0; *(LAS u32x4*)(kdst + 16) = w1;
;         w0.x = cvt_pk_bf16(o2[0], o2[1]); w0.y = cvt_pk_bf16(o2[2], o2[3]); w0.z = cvt_pk_bf16(o2[4], o2[5]); w0.w = cvt_pk_bf16(o2[6], o2[7]);
;         w1.x = cvt_pk_bf16(o2[8], o2[9]); w1.y = cvt_pk_bf16(o2[10], o2[11]); w1.z = cvt_pk_bf16(o2[12], o2[13]); w1.w = cvt_pk_bf16(o2[14], o2[15]);
;     ...
;         const float* gp = lng + gg * 128 + 32 * q4; const float* bp = lnb + gg * 128 + 32 * q4;
	v_mov_b32_e32 v102, v123
	v_pk_mul_f32 v[52:53], v[50:51], v[122:123]
	v_pk_mul_f32 v[50:51], v[50:51], v[102:103]
	v_mov_b32_e32 v197, v100
	v_add_f32_e32 v95, v51, v50
	v_pk_mul_f32 v[50:51], v[54:55], v[194:195] op_sel_hi:[0,1]
	v_mov_b32_e32 v198, v104
	v_mov_b32_e32 v199, v124
	v_pk_mul_f32 v[50:51], v[50:51], v[196:197]
	v_sub_f32_e32 v56, v52, v53
	v_pk_mul_f32 v[52:53], v[50:51], v[198:199]
	v_mov_b32_e32 v100, v97
	v_sub_f32_e32 v57, v52, v53
	v_mov_b32_e32 v52, v124
	v_mov_b32_e32 v53, v104
	v_pk_mul_f32 v[50:51], v[50:51], v[52:53]
	v_mov_b32_e32 v124, v105
	v_add_f32_e32 v98, v51, v50
	v_pk_mul_f32 v[50:51], v[54:55], v[200:201] op_sel_hi:[0,1]
	v_pk_mul_f32 v[50:51], v[50:51], v[100:101]
	v_mov_b32_e32 v104, v125
	v_pk_mul_f32 v[52:53], v[50:51], v[124:125]
	v_pk_mul_f32 v[50:51], v[50:51], v[104:105]
	v_mov_b32_e32 v191, v82
	v_add_f32_e32 v99, v51, v50
	v_pk_mul_f32 v[50:51], v[54:55], v[188:189] op_sel_hi:[0,1]
	v_mov_b32_e32 v192, v90
	v_mov_b32_e32 v193, v118
	v_pk_mul_f32 v[50:51], v[50:51], v[190:191]
	v_sub_f32_e32 v97, v52, v53
	v_pk_mul_f32 v[52:53], v[50:51], v[192:193]
	v_mov_b32_e32 v82, v79
	v_sub_f32_e32 v100, v52, v53
	v_mov_b32_e32 v52, v118
	v_mov_b32_e32 v53, v90
	v_pk_mul_f32 v[50:51], v[50:51], v[52:53]
	v_mov_b32_e32 v118, v91
	v_add_f32_e32 v101, v51, v50
	v_pk_mul_f32 v[50:51], v[54:55], v[58:59] op_sel_hi:[0,1]
	v_pk_mul_f32 v[50:51], v[50:51], v[82:83]
	v_mov_b32_e32 v90, v119
	v_pk_mul_f32 v[52:53], v[50:51], v[118:119]
	v_pk_mul_f32 v[50:51], v[50:51], v[90:91]
	v_mov_b32_e32 v157, v84
	v_add_f32_e32 v59, v51, v50
	v_pk_mul_f32 v[50:51], v[54:55], v[154:155] op_sel_hi:[0,1]
	v_mov_b32_e32 v158, v92
	v_mov_b32_e32 v159, v120
	v_pk_mul_f32 v[50:51], v[50:51], v[156:157]
	v_sub_f32_e32 v58, v52, v53
	v_pk_mul_f32 v[52:53], v[50:51], v[158:159]
	v_mov_b32_e32 v84, v81
	v_sub_f32_e32 v79, v52, v53
	v_mov_b32_e32 v52, v120
	v_mov_b32_e32 v53, v92
	v_pk_mul_f32 v[50:51], v[50:51], v[52:53]
	v_mov_b32_e32 v120, v93
	v_add_f32_e32 v82, v51, v50
	v_pk_mul_f32 v[50:51], v[54:55], v[64:65] op_sel_hi:[0,1]
	v_pk_mul_f32 v[50:51], v[50:51], v[84:85]
	v_mov_b32_e32 v92, v121
	v_pk_mul_f32 v[52:53], v[50:51], v[120:121]
	v_pk_mul_f32 v[50:51], v[50:51], v[92:93]
	v_mov_b32_e32 v151, v70
	v_add_f32_e32 v65, v51, v50
	v_pk_mul_f32 v[50:51], v[54:55], v[148:149] op_sel_hi:[0,1]
	v_mov_b32_e32 v152, v74
	v_mov_b32_e32 v153, v86
	v_pk_mul_f32 v[50:51], v[50:51], v[150:151]
	v_sub_f32_e32 v64, v52, v53
	v_pk_mul_f32 v[52:53], v[50:51], v[152:153]
	v_mov_b32_e32 v70, v67
	v_sub_f32_e32 v81, v52, v53
	v_mov_b32_e32 v52, v86
	v_mov_b32_e32 v53, v74
	v_pk_mul_f32 v[50:51], v[50:51], v[52:53]
	v_mov_b32_e32 v86, v75
	v_add_f32_e32 v83, v51, v50
	v_pk_mul_f32 v[50:51], v[54:55], v[60:61] op_sel_hi:[0,1]
	v_pk_mul_f32 v[50:51], v[50:51], v[70:71]
	v_mov_b32_e32 v74, v87
	v_pk_mul_f32 v[52:53], v[50:51], v[86:87]
	v_pk_mul_f32 v[50:51], v[50:51], v[74:75]
	v_mov_b32_e32 v145, v72
	v_add_f32_e32 v61, v51, v50
	v_pk_mul_f32 v[50:51], v[54:55], v[142:143] op_sel_hi:[0,1]
	v_mov_b32_e32 v146, v76
	v_mov_b32_e32 v147, v88
	v_pk_mul_f32 v[50:51], v[50:51], v[144:145]
	v_sub_f32_e32 v60, v52, v53
	v_pk_mul_f32 v[52:53], v[50:51], v[146:147]
	v_mov_b32_e32 v72, v69
	v_lshl_add_u32 v182, v165, 2, s4
	global_load_dwordx4 v[144:147], v182, s[36:37] offset:0
	global_load_dwordx4 v[148:151], v182, s[36:37] offset:16
	global_load_dwordx4 v[152:155], v182, s[36:37] offset:32
	global_load_dwordx4 v[156:159], v182, s[36:37] offset:48
	global_load_dwordx4 v[184:187], v182, s[36:37] offset:64
	global_load_dwordx4 v[188:191], v182, s[36:37] offset:80
	global_load_dwordx4 v[192:195], v182, s[36:37] offset:96
	global_load_dwordx4 v[196:199], v182, s[36:37] offset:112
	global_load_dwordx4 v[218:221], v182, s[18:19] offset:0
	global_load_dwordx4 v[222:225], v182, s[18:19] offset:16
	global_load_dwordx4 v[226:229], v182, s[18:19] offset:32
	global_load_dwordx4 v[230:233], v182, s[18:19] offset:48
	global_load_dwordx4 v[234:237], v182, s[18:19] offset:64
	global_load_dwordx4 v[238:241], v182, s[18:19] offset:80
	global_load_dwordx4 v[242:245], v182, s[18:19] offset:96
	global_load_dwordx4 v[200:203], v182, s[18:19] offset:112
	v_sub_f32_e32 v67, v52, v53
	v_mov_b32_e32 v52, v88
	v_mov_b32_e32 v53, v76
	v_pk_mul_f32 v[50:51], v[50:51], v[52:53]
	v_mov_b32_e32 v88, v77
	v_add_f32_e32 v70, v51, v50
	v_pk_mul_f32 v[50:51], v[54:55], v[140:141] op_sel_hi:[0,1]
	v_pk_mul_f32 v[50:51], v[50:51], v[72:73]
	v_mov_b32_e32 v76, v89
	v_pk_mul_f32 v[52:53], v[50:51], v[88:89]
	v_pk_mul_f32 v[50:51], v[50:51], v[76:77]
	v_sub_f32_e32 v69, v52, v53
	v_add_f32_e32 v71, v51, v50
	v_mul_lo_u32 v50, v167, s59
	v_add3_u32 v0, 0, v50, v0
	v_cvt_pk_bf16_f32 v50, v55, v63
	v_cvt_pk_bf16_f32 v51, v68, v80
	v_cvt_pk_bf16_f32 v52, v96, v56
	v_cvt_pk_bf16_f32 v53, v57, v97
	v_cvt_pk_bf16_f32 v54, v100, v58
	v_cvt_pk_bf16_f32 v55, v79, v64
	v_cvt_pk_bf16_f32 v56, v81, v60
	v_cvt_pk_bf16_f32 v57, v67, v69
	s_waitcnt vmcnt(20)
; __device__ __forceinline__ unsigned cvt_pk_bf16(float lo, float hi) { unsigned r; asm volatile("v_cvt_pk_bf16_f32 %0, %1, %2" : "=v"(r) : "v"(lo), "v"(hi)); return r; }
; __device__ __forceinline__ float gelu_f(float x) { const float y2 = 1.5957691216057308f * x * (1.0f + 0.044715f * x * x); return x * sigmoid_f(y2); }
; #define LAS __attribute__((address_space(3)))
; __device__ __forceinline__ void unpack8(const u32x4 w, float* f) { f[0] = bf_lo(w.x); f[1] = bf_hi(w.x); f[2] = bf_lo(w.y); f[3] = bf_hi(w.y); f[4] = bf_lo(w.z); f[5] = bf_hi(w.z); f[6] = bf_lo(w.w); f[7] = bf_hi(w.w); }
; __device__ __forceinline__ void p2_block(LAS unsigned char* lds, const bf16_t* __restrict__ PROJ, bf16_t* __restrict__ ATT, bf16_t* __restrict__ SGU, const float* __restrict__ qn, const float* __restrict__ kn, ...
;     ...
;         *(LAS u32x4*)kdst = w0; *(LAS u32x4*)(kdst + 16) = w1;
;         w0.x = cvt_pk_bf16(o2[0], o2[1]); w0.y = cvt_pk_bf16(o2[2], o2[3]); w0.z = cvt_pk_bf16(o2[4], o2[5]); w0.w = cvt_pk_bf16(o2[6], o2[7]);
;         w1.x = cvt_pk_bf16(o2[8], o2[9]); w1.y = cvt_pk_bf16(o2[10], o2[11]); w1.z = cvt_pk_bf16(o2[12], o2[13]); w1.w = cvt_pk_bf16(o2[14], o2[15]);
;         *(LAS u32x4*)(kdst + 64) = w0; *(LAS u32x4*)(kdst + 80) = w1;
;     ...
; #pragma unroll
;         for (int c4 = 0; c4 < 4; ++c4) unpack8(sv[gi][c4], v + 8 * c4);
;         float sm = 0.f;
; #pragma unroll
;         for (int j = 0; j < 32; ++j) { v[j] = gelu_f(v[j]); sm += v[j]; }
	v_lshlrev_b32_e32 v73, 16, v46
	ds_write_b128 v0, v[50:53]
	ds_write_b128 v0, v[54:57] offset:16
	v_cvt_pk_bf16_f32 v50, v62, v66
	v_cvt_pk_bf16_f32 v51, v78, v94
	v_cvt_pk_bf16_f32 v52, v106, v95
	v_cvt_pk_bf16_f32 v53, v98, v99
	v_cvt_pk_bf16_f32 v54, v101, v59
	v_cvt_pk_bf16_f32 v55, v82, v65
	v_cvt_pk_bf16_f32 v56, v83, v61
	v_cvt_pk_bf16_f32 v57, v70, v71
	v_lshlrev_b32_e32 v70, 16, v48
	v_and_b32_e32 v69, 0xffff0000, v48
	v_lshlrev_b32_e32 v68, 16, v49
	v_and_b32_e32 v67, 0xffff0000, v49
	v_lshlrev_b32_e32 v66, 16, v42
	v_and_b32_e32 v65, 0xffff0000, v42
	v_lshlrev_b32_e32 v64, 16, v43
	v_and_b32_e32 v63, 0xffff0000, v43
	v_lshlrev_b32_e32 v62, 16, v44
	v_and_b32_e32 v61, 0xffff0000, v44
	v_lshlrev_b32_e32 v60, 16, v45
	v_and_b32_e32 v59, 0xffff0000, v45
	v_lshlrev_b32_e32 v49, 16, v40
	v_and_b32_e32 v48, 0xffff0000, v40
	v_lshlrev_b32_e32 v45, 16, v41
	v_and_b32_e32 v44, 0xffff0000, v41
	v_lshlrev_b32_e32 v43, 16, v34
	v_and_b32_e32 v42, 0xffff0000, v34
	v_lshlrev_b32_e32 v41, 16, v35
	v_and_b32_e32 v40, 0xffff0000, v35
	v_lshlrev_b32_e32 v35, 16, v37
	v_and_b32_e32 v34, 0xffff0000, v37
	v_mul_f32_e32 v37, 0x3d372713, v73
	ds_write_b128 v0, v[50:53] offset:64
	ds_write_b128 v0, v[54:57] offset:80
	v_lshlrev_b32_e32 v58, 16, v38
	v_and_b32_e32 v57, 0xffff0000, v38
	v_lshlrev_b32_e32 v56, 16, v39
	v_and_b32_e32 v55, 0xffff0000, v39
	v_lshlrev_b32_e32 v39, 16, v36
	v_and_b32_e32 v38, 0xffff0000, v36
	v_mul_f32_e32 v36, 0x3fcc422a, v73
	v_fma_f32 v37, v37, v73, 1.0
	v_mul_f32_e32 v36, v36, v37
	v_mul_f32_e32 v36, 0xbfb8aa3b, v36
	v_exp_f32_e32 v36, v36
	v_and_b32_e32 v74, 0xffff0000, v46
	v_mul_f32_e32 v37, 0x3d372713, v74
	v_fma_f32 v37, v37, v74, 1.0
	v_add_f32_e32 v36, 1.0, v36
	v_rcp_f32_e32 v75, v36
	v_mul_f32_e32 v36, 0x3fcc422a, v74
	v_mul_f32_e32 v36, v36, v37
	v_mul_f32_e32 v36, 0xbfb8aa3b, v36
	v_exp_f32_e32 v36, v36
	v_lshlrev_b32_e32 v72, 16, v47
	v_mul_f32_e32 v37, 0x3d372713, v72
	v_fma_f32 v37, v37, v72, 1.0
	v_add_f32_e32 v36, 1.0, v36
	v_rcp_f32_e32 v76, v36
	v_mul_f32_e32 v36, 0x3fcc422a, v72
	v_mul_f32_e32 v36, v36, v37
	v_mul_f32_e32 v36, 0xbfb8aa3b, v36
	v_exp_f32_e32 v36, v36
	v_and_b32_e32 v71, 0xffff0000, v47
	v_mul_f32_e32 v37, 0x3d372713, v71
	v_fma_f32 v37, v37, v71, 1.0
	v_add_f32_e32 v36, 1.0, v36
	v_rcp_f32_e32 v77, v36
	v_mul_f32_e32 v36, 0x3fcc422a, v71
	v_mul_f32_e32 v36, v36, v37
	v_mul_f32_e32 v36, 0xbfb8aa3b, v36
	v_exp_f32_e32 v36, v36
	v_mul_f32_e32 v37, 0x3d372713, v70
	v_fma_f32 v37, v37, v70, 1.0
	v_fma_f32 v46, v75, v73, 0
	v_add_f32_e32 v36, 1.0, v36
	v_rcp_f32_e32 v78, v36
	v_mul_f32_e32 v36, 0x3fcc422a, v70
	v_mul_f32_e32 v36, v36, v37
	v_mul_f32_e32 v36, 0xbfb8aa3b, v36
	v_exp_f32_e32 v36, v36
	v_mul_f32_e32 v37, 0x3d372713, v69
	v_fma_f32 v37, v37, v69, 1.0
	v_fmac_f32_e32 v46, v76, v74
	v_add_f32_e32 v36, 1.0, v36
	v_rcp_f32_e32 v79, v36
	v_mul_f32_e32 v36, 0x3fcc422a, v69
	v_mul_f32_e32 v36, v36, v37
	v_mul_f32_e32 v36, 0xbfb8aa3b, v36
	v_exp_f32_e32 v36, v36
	v_mul_f32_e32 v37, 0x3d372713, v68
	v_fma_f32 v37, v37, v68, 1.0
	v_fmac_f32_e32 v46, v77, v72
	v_add_f32_e32 v36, 1.0, v36
	v_rcp_f32_e32 v80, v36
	v_mul_f32_e32 v36, 0x3fcc422a, v68
	v_mul_f32_e32 v36, v36, v37
	v_mul_f32_e32 v36, 0xbfb8aa3b, v36
	v_exp_f32_e32 v36, v36
	v_mul_f32_e32 v37, 0x3d372713, v67
	v_fma_f32 v37, v37, v67, 1.0
	v_fmac_f32_e32 v46, v78, v71
	v_add_f32_e32 v36, 1.0, v36
	v_rcp_f32_e32 v81, v36
	v_mul_f32_e32 v36, 0x3fcc422a, v67
	v_mul_f32_e32 v36, v36, v37
	v_mul_f32_e32 v36, 0xbfb8aa3b, v36
	v_exp_f32_e32 v36, v36
	v_mul_f32_e32 v37, 0x3d372713, v66
	v_fma_f32 v37, v37, v66, 1.0
	v_fmac_f32_e32 v46, v79, v70
	v_add_f32_e32 v36, 1.0, v36
	v_rcp_f32_e32 v82, v36
	v_mul_f32_e32 v36, 0x3fcc422a, v66
	v_mul_f32_e32 v36, v36, v37
	v_mul_f32_e32 v36, 0xbfb8aa3b, v36
	v_exp_f32_e32 v36, v36
	v_mul_f32_e32 v37, 0x3d372713, v65
	v_fma_f32 v37, v37, v65, 1.0
	v_fmac_f32_e32 v46, v80, v69
	v_add_f32_e32 v36, 1.0, v36
	v_rcp_f32_e32 v84, v36
	v_mul_f32_e32 v36, 0x3fcc422a, v65
	v_mul_f32_e32 v36, v36, v37
	v_mul_f32_e32 v36, 0xbfb8aa3b, v36
	v_exp_f32_e32 v36, v36
	v_mul_f32_e32 v37, 0x3d372713, v64
	v_fma_f32 v37, v37, v64, 1.0
	v_fmac_f32_e32 v46, v81, v68
	v_add_f32_e32 v36, 1.0, v36
	v_rcp_f32_e32 v85, v36
	v_mul_f32_e32 v36, 0x3fcc422a, v64
	v_mul_f32_e32 v36, v36, v37
	v_mul_f32_e32 v36, 0xbfb8aa3b, v36
	v_exp_f32_e32 v36, v36
	v_mul_f32_e32 v37, 0x3d372713, v63
	v_fma_f32 v37, v37, v63, 1.0
	v_fmac_f32_e32 v46, v82, v67
	v_add_f32_e32 v36, 1.0, v36
	v_rcp_f32_e32 v86, v36
	v_mul_f32_e32 v36, 0x3fcc422a, v63
	v_mul_f32_e32 v36, v36, v37
	v_mul_f32_e32 v36, 0xbfb8aa3b, v36
	v_exp_f32_e32 v36, v36
	v_mul_f32_e32 v37, 0x3d372713, v62
	v_fma_f32 v37, v37, v62, 1.0
	v_fmac_f32_e32 v46, v84, v66
	v_add_f32_e32 v36, 1.0, v36
	v_rcp_f32_e32 v87, v36
	v_mul_f32_e32 v36, 0x3fcc422a, v62
	v_mul_f32_e32 v36, v36, v37
	v_mul_f32_e32 v36, 0xbfb8aa3b, v36
	v_exp_f32_e32 v36, v36
	v_mul_f32_e32 v37, 0x3d372713, v61
	v_fma_f32 v37, v37, v61, 1.0
	v_fmac_f32_e32 v46, v85, v65
	v_add_f32_e32 v36, 1.0, v36
	v_rcp_f32_e32 v88, v36
	v_mul_f32_e32 v36, 0x3fcc422a, v61
	v_mul_f32_e32 v36, v36, v37
	v_mul_f32_e32 v36, 0xbfb8aa3b, v36
	v_exp_f32_e32 v36, v36
	v_mul_f32_e32 v37, 0x3d372713, v60
	v_fma_f32 v37, v37, v60, 1.0
	v_fmac_f32_e32 v46, v86, v64
	v_add_f32_e32 v36, 1.0, v36
	v_rcp_f32_e32 v89, v36
	v_mul_f32_e32 v36, 0x3fcc422a, v60
	v_mul_f32_e32 v36, v36, v37
	v_mul_f32_e32 v36, 0xbfb8aa3b, v36
	v_exp_f32_e32 v36, v36
	v_mul_f32_e32 v37, 0x3d372713, v59
	v_fma_f32 v37, v37, v59, 1.0
	v_mul_f32_e32 v47, 0x3d372713, v42
	v_add_f32_e32 v36, 1.0, v36
	v_rcp_f32_e32 v90, v36
	v_mul_f32_e32 v36, 0x3fcc422a, v59
	v_mul_f32_e32 v36, v36, v37
; __device__ __forceinline__ float gelu_f(float x) { const float y2 = 1.5957691216057308f * x * (1.0f + 0.044715f * x * x); return x * sigmoid_f(y2); }
; #define LAS __attribute__((address_space(3)))
; __device__ __forceinline__ void unpack8(const u32x4 w, float* f) { f[0] = bf_lo(w.x); f[1] = bf_hi(w.x); f[2] = bf_lo(w.y); f[3] = bf_hi(w.y); f[4] = bf_lo(w.z); f[5] = bf_hi(w.z); f[6] = bf_lo(w.w); f[7] = bf_hi(w.w); }
; __device__ __forceinline__ void p2_block(LAS unsigned char* lds, const bf16_t* __restrict__ PROJ, bf16_t* __restrict__ ATT, bf16_t* __restrict__ SGU, const float* __restrict__ qn, const float* __restrict__ kn, ...
;     ...
;         for (int c4 = 0; c4 < 4; ++c4) { u32x4 t = vv[c4]; if (s < 0) t = (u32x4){0u, 0u, 0u, 0u};
;             LAS unsigned char* vd = VT + (32 * h + 8 * c4) * VT_STRIDE + kk * 2;
;             *(LAS unsigned short*)(vd + 0 * VT_STRIDE) = (unsigned short)(t.x & 0xffffu); *(LAS unsigned short*)(vd + 1 * VT_STRIDE) = (unsigned short)(t.x >> 16);
;             *(LAS unsigned short*)(vd + 2 * VT_STRIDE) = (unsigned short)(t.y & 0xffffu); *(LAS unsigned short*)(vd + 3 * VT_STRIDE) = (unsigned short)(t.y >> 16);
;             *(LAS unsigned short*)(vd + 4 * VT_STRIDE) = (unsigned short)(t.z & 0xffffu); *(LAS unsigned short*)(vd + 5 * VT_STRIDE) = (unsigned short)(t.z >> 16);
;             *(LAS unsigned short*)(vd + 6 * VT_STRIDE) = (unsigned short)(t.w & 0xffffu); *(LAS unsigned short*)(vd + 7 * VT_STRIDE) = (unsigned short)(t.w >> 16); }
;     ...
;         float v[32];
; #pragma unroll
;         for (int c4 = 0; c4 < 4; ++c4) unpack8(sv[gi][c4], v + 8 * c4);
;         float sm = 0.f;
; #pragma unroll
;         for (int j = 0; j < 32; ++j) { v[j] = gelu_f(v[j]); sm += v[j]; }
	v_mul_f32_e32 v36, 0xbfb8aa3b, v36
	v_exp_f32_e32 v36, v36
	v_mul_f32_e32 v37, 0x3d372713, v58
	v_fma_f32 v37, v37, v58, 1.0
	v_fmac_f32_e32 v46, v87, v63
	v_add_f32_e32 v36, 1.0, v36
	v_rcp_f32_e32 v91, v36
	v_mul_f32_e32 v36, 0x3fcc422a, v58
	v_mul_f32_e32 v36, v36, v37
	v_mul_f32_e32 v36, 0xbfb8aa3b, v36
	v_exp_f32_e32 v36, v36
	v_mul_f32_e32 v37, 0x3d372713, v57
	v_fma_f32 v37, v37, v57, 1.0
	v_fma_f32 v47, v47, v42, 1.0
	v_add_f32_e32 v36, 1.0, v36
	v_rcp_f32_e32 v98, v36
	v_mul_f32_e32 v36, 0x3fcc422a, v57
	v_mul_f32_e32 v36, v36, v37
	v_mul_f32_e32 v36, 0xbfb8aa3b, v36
	v_exp_f32_e32 v36, v36
	v_mul_f32_e32 v37, 0x3d372713, v56
	v_fma_f32 v37, v37, v56, 1.0
	v_fmac_f32_e32 v46, v88, v62
	v_add_f32_e32 v36, 1.0, v36
	v_rcp_f32_e32 v99, v36
	v_mul_f32_e32 v36, 0x3fcc422a, v56
	v_mul_f32_e32 v36, v36, v37
	v_mul_f32_e32 v36, 0xbfb8aa3b, v36
	v_exp_f32_e32 v36, v36
	v_mul_f32_e32 v37, 0x3d372713, v55
	v_fma_f32 v37, v37, v55, 1.0
	v_fmac_f32_e32 v46, v89, v61
	v_add_f32_e32 v36, 1.0, v36
	v_rcp_f32_e32 v100, v36
	v_mul_f32_e32 v36, 0x3fcc422a, v55
	v_mul_f32_e32 v36, v36, v37
	v_mul_f32_e32 v36, 0xbfb8aa3b, v36
	v_exp_f32_e32 v36, v36
	v_mul_f32_e32 v37, 0x3d372713, v49
	v_fma_f32 v37, v37, v49, 1.0
	v_fmac_f32_e32 v46, v90, v60
	v_add_f32_e32 v36, 1.0, v36
	v_rcp_f32_e32 v101, v36
	v_mul_f32_e32 v36, 0x3fcc422a, v49
	v_mul_f32_e32 v36, v36, v37
	v_mul_f32_e32 v36, 0xbfb8aa3b, v36
	v_exp_f32_e32 v36, v36
	v_mul_f32_e32 v37, 0x3d372713, v48
	v_fma_f32 v37, v37, v48, 1.0
	v_fmac_f32_e32 v46, v91, v59
	v_add_f32_e32 v36, 1.0, v36
	v_rcp_f32_e32 v102, v36
	v_mul_f32_e32 v36, 0x3fcc422a, v48
	v_mul_f32_e32 v36, v36, v37
	v_mul_f32_e32 v36, 0xbfb8aa3b, v36
	v_exp_f32_e32 v36, v36
	v_mul_f32_e32 v37, 0x3d372713, v45
	v_fma_f32 v37, v37, v45, 1.0
	v_fmac_f32_e32 v46, v98, v58
	v_add_f32_e32 v36, 1.0, v36
	v_rcp_f32_e32 v103, v36
	v_mul_f32_e32 v36, 0x3fcc422a, v45
	v_mul_f32_e32 v36, v36, v37
	v_mul_f32_e32 v36, 0xbfb8aa3b, v36
	v_exp_f32_e32 v36, v36
	v_mul_f32_e32 v37, 0x3d372713, v44
	v_fma_f32 v37, v37, v44, 1.0
	v_fmac_f32_e32 v46, v99, v57
	v_add_f32_e32 v36, 1.0, v36
	v_rcp_f32_e32 v104, v36
	v_mul_f32_e32 v36, 0x3fcc422a, v44
	v_mul_f32_e32 v36, v36, v37
	v_mul_f32_e32 v36, 0xbfb8aa3b, v36
	v_exp_f32_e32 v36, v36
	v_mul_f32_e32 v37, 0x3d372713, v43
	v_fma_f32 v37, v37, v43, 1.0
	v_fmac_f32_e32 v46, v100, v56
	v_add_f32_e32 v36, 1.0, v36
	v_rcp_f32_e32 v105, v36
	v_mul_f32_e32 v36, 0x3fcc422a, v43
	v_mul_f32_e32 v36, v36, v37
	v_mul_f32_e32 v36, 0xbfb8aa3b, v36
	v_exp_f32_e32 v36, v36
	v_fmac_f32_e32 v46, v101, v55
	v_fmac_f32_e32 v46, v102, v49
	v_fmac_f32_e32 v46, v103, v48
	v_add_f32_e32 v36, 1.0, v36
	v_rcp_f32_e32 v37, v36
	v_mul_f32_e32 v36, 0x3fcc422a, v42
	v_mul_f32_e32 v36, v36, v47
	v_mul_f32_e32 v36, 0xbfb8aa3b, v36
	v_exp_f32_e32 v36, v36
	v_fmac_f32_e32 v46, v104, v45
	v_fmac_f32_e32 v46, v105, v44
	v_mul_f32_e32 v47, 0x3d372713, v41
	v_add_f32_e32 v36, 1.0, v36
	v_rcp_f32_e32 v36, v36
	v_fma_f32 v47, v47, v41, 1.0
	v_mul_f32_e32 v94, 0x3d372713, v38
	v_fma_f32 v94, v94, v38, 1.0
	v_pk_mul_f32 v[92:93], v[36:37], v[42:43]
	v_mul_f32_e32 v96, 0x3d372713, v34
	v_add_f32_e32 v46, v93, v46
	v_add_f32_e32 v83, v92, v46
	v_mul_f32_e32 v46, 0x3fcc422a, v41
	v_mul_f32_e32 v46, v46, v47
	v_mul_f32_e32 v46, 0xbfb8aa3b, v46
	v_exp_f32_e32 v46, v46
	v_mul_f32_e32 v92, 0x3d372713, v40
	v_fma_f32 v92, v92, v40, 1.0
	v_fma_f32 v96, v96, v34, 1.0
	v_add_f32_e32 v46, 1.0, v46
	v_rcp_f32_e32 v47, v46
	v_mul_f32_e32 v46, 0x3fcc422a, v40
	v_mul_f32_e32 v46, v46, v92
	v_mul_f32_e32 v46, 0xbfb8aa3b, v46
	v_exp_f32_e32 v46, v46
	v_and_b32_e32 v0, -2, v160
	v_mul_u32_u24_e32 v50, 0x4200, v166
	s_waitcnt vmcnt(16)
	v_cndmask_b32_e64 v18, v18, 0, vcc
	v_add_f32_e32 v46, 1.0, v46
	v_rcp_f32_e32 v46, v46
	v_add3_u32 v0, 0, v0, v50
	v_cndmask_b32_e64 v14, v14, 0, vcc
	v_cndmask_b32_e64 v10, v10, 0, vcc
	v_pk_mul_f32 v[92:93], v[46:47], v[40:41]
	v_cndmask_b32_e64 v6, v6, 0, vcc
	v_add_f32_e32 v83, v93, v83
	v_mul_f32_e32 v93, 0x3d372713, v39
	v_add_f32_e32 v83, v92, v83
	v_mul_f32_e32 v92, 0x3fcc422a, v39
	v_fma_f32 v93, v93, v39, 1.0
	v_mul_f32_e32 v92, v92, v93
	v_mul_f32_e32 v92, 0xbfb8aa3b, v92
	v_exp_f32_e32 v92, v92
	v_cndmask_b32_e64 v21, v21, 0, vcc
	v_cndmask_b32_e64 v20, v20, 0, vcc
	v_cndmask_b32_e64 v19, v19, 0, vcc
	v_add_f32_e32 v92, 1.0, v92
	v_rcp_f32_e32 v93, v92
	v_mul_f32_e32 v92, 0x3fcc422a, v38
	v_mul_f32_e32 v92, v92, v94
	v_mul_f32_e32 v92, 0xbfb8aa3b, v92
	v_exp_f32_e32 v92, v92
	ds_write_b16 v0, v18 offset:36864
	ds_write_b16_d16_hi v0, v18 offset:37392
	ds_write_b16 v0, v19 offset:37920
	ds_write_b16_d16_hi v0, v19 offset:38448
	ds_write_b16 v0, v20 offset:38976
	ds_write_b16_d16_hi v0, v20 offset:39504
	ds_write_b16 v0, v21 offset:40032
	ds_write_b16_d16_hi v0, v21 offset:40560
	v_cndmask_b32_e64 v17, v17, 0, vcc
	v_cndmask_b32_e64 v16, v16, 0, vcc
	v_add_f32_e32 v92, 1.0, v92
	v_rcp_f32_e32 v92, v92
	v_cndmask_b32_e64 v15, v15, 0, vcc
	ds_write_b16 v0, v14 offset:41088
	ds_write_b16_d16_hi v0, v14 offset:41616
	ds_write_b16 v0, v15 offset:42144
	ds_write_b16_d16_hi v0, v15 offset:42672
	ds_write_b16 v0, v16 offset:43200
	ds_write_b16_d16_hi v0, v16 offset:43728
	ds_write_b16 v0, v17 offset:44256
	ds_write_b16_d16_hi v0, v17 offset:44784
	v_cndmask_b32_e64 v13, v13, 0, vcc
	v_pk_mul_f32 v[94:95], v[92:93], v[38:39]
	v_cndmask_b32_e64 v12, v12, 0, vcc
	v_add_f32_e32 v83, v95, v83
	v_mul_f32_e32 v95, 0x3d372713, v35
	v_add_f32_e32 v83, v94, v83
	v_mul_f32_e32 v94, 0x3fcc422a, v35
	v_fma_f32 v95, v95, v35, 1.0
	v_mul_f32_e32 v94, v94, v95
	v_mul_f32_e32 v94, 0xbfb8aa3b, v94
	v_exp_f32_e32 v94, v94
	v_cndmask_b32_e64 v11, v11, 0, vcc
; __device__ __forceinline__ float gelu_f(float x) { const float y2 = 1.5957691216057308f * x * (1.0f + 0.044715f * x * x); return x * sigmoid_f(y2); }
; __device__ __forceinline__ void p2_block(LAS unsigned char* lds, const bf16_t* __restrict__ PROJ, bf16_t* __restrict__ ATT, bf16_t* __restrict__ SGU, const float* __restrict__ qn, const float* __restrict__ kn, ...
;     ...
;             for (int c4 = 0; c4 < 4; ++c4) sv[1][c4] = *(const u32x4*)(svsrc + 128 + 8 * c4); }
;     ...
;         for (int j = 0; j < 32; ++j) { v[j] = gelu_f(v[j]); sm += v[j]; }
;         sm += __shfl_xor(sm, 1); sm += __shfl_xor(sm, 2);
;         const float mu = sm * (1.0f / 128.0f); float q = 0.f;
; #pragma unroll
;         for (int j = 0; j < 32; ++j) { v[j] -= mu; q += v[j] * v[j]; }
;         q += __shfl_xor(q, 1); q += __shfl_xor(q, 2);
;         const float rstd = rsqrtf(q * (1.0f / 128.0f) + pg8::EPS);
	ds_write_b16 v0, v10 offset:45312
	ds_write_b16_d16_hi v0, v10 offset:45840
	ds_write_b16 v0, v11 offset:46368
	ds_write_b16_d16_hi v0, v11 offset:46896
	ds_write_b16 v0, v12 offset:47424
	ds_write_b16_d16_hi v0, v12 offset:47952
	ds_write_b16 v0, v13 offset:48480
	ds_write_b16_d16_hi v0, v13 offset:49008
	v_cndmask_b32_e64 v9, v9, 0, vcc
	v_add_f32_e32 v94, 1.0, v94
	v_rcp_f32_e32 v95, v94
	v_mul_f32_e32 v94, 0x3fcc422a, v34
	v_mul_f32_e32 v94, v94, v96
	v_mul_f32_e32 v94, 0xbfb8aa3b, v94
	v_exp_f32_e32 v94, v94
	v_cndmask_b32_e64 v8, v8, 0, vcc
	v_cndmask_b32_e64 v7, v7, 0, vcc
	ds_write_b16 v0, v6 offset:49536
	ds_write_b16_d16_hi v0, v6 offset:50064
	ds_write_b16 v0, v7 offset:50592
	ds_write_b16_d16_hi v0, v7 offset:51120
	ds_write_b16 v0, v8 offset:51648
	ds_write_b16_d16_hi v0, v8 offset:52176
	ds_write_b16 v0, v9 offset:52704
	ds_write_b16_d16_hi v0, v9 offset:53232
	v_add_f32_e32 v94, 1.0, v94
	v_rcp_f32_e32 v94, v94
	v_xor_b32_e32 v0, 2, v211
	v_cmp_lt_i32_e32 vcc, v0, v133
	v_lshlrev_b32_e32 v6, 1, v136
	v_pk_mul_f32 v[96:97], v[94:95], v[34:35]
	v_cndmask_b32_e32 v0, v211, v0, vcc
	v_add_f32_e32 v83, v97, v83
	v_add_f32_e32 v83, v96, v83
	s_nop 1
	v_mov_b32_dpp v96, v83 quad_perm:[1,0,3,2] row_mask:0xf bank_mask:0xf
	v_lshlrev_b32_e32 v54, 2, v0
	v_lshlrev_b32_e32 v0, 2, v165
	v_lshl_add_u64 v[50:51], s[36:37], 0, v[0:1]
	v_lshl_add_u64 v[52:53], s[18:19], 0, v[0:1]
	s_waitcnt lgkmcnt(0)
	v_add_f32_e32 v83, v83, v96
	s_nop 1
	v_mov_b32_dpp v96, v83 quad_perm:[2,3,0,1] row_mask:0xf bank_mask:0xf
	v_mul_u32_u24_e32 v0, 0x110, v165
	v_add3_u32 v0, 0, v0, v6
	global_load_dwordx4 v[6:9], v[138:139], off offset:304
	global_load_dwordx4 v[10:13], v[138:139], off offset:288
	global_load_dwordx4 v[14:17], v[138:139], off offset:272
	global_load_dwordx4 v[18:21], v[138:139], off offset:256
	s_ashr_i32 s43, s42, 31
	s_waitcnt lgkmcnt(0)
	v_add_f32_e32 v83, v83, v96
	v_mul_f32_e32 v96, 0x3c000000, v83
	v_fma_f32 v83, v76, v74, -v96
	v_fma_f32 v97, v75, v73, -v96
	v_mul_f32_e32 v106, v83, v83
	v_fmac_f32_e32 v106, v97, v97
	v_fma_f32 v77, v77, v72, -v96
	v_fmac_f32_e32 v106, v77, v77
	v_fma_f32 v76, v78, v71, -v96
	v_fmac_f32_e32 v106, v76, v76
	v_fma_f32 v75, v79, v70, -v96
	v_fmac_f32_e32 v106, v75, v75
	v_fma_f32 v74, v80, v69, -v96
	v_fmac_f32_e32 v106, v74, v74
	v_fma_f32 v73, v81, v68, -v96
	v_fmac_f32_e32 v106, v73, v73
	v_fma_f32 v72, v82, v67, -v96
	v_fmac_f32_e32 v106, v72, v72
	v_fma_f32 v71, v84, v66, -v96
	v_fmac_f32_e32 v106, v71, v71
	v_fma_f32 v70, v85, v65, -v96
	v_fmac_f32_e32 v106, v70, v70
	v_fma_f32 v69, v86, v64, -v96
	v_fmac_f32_e32 v106, v69, v69
	v_fma_f32 v68, v87, v63, -v96
	v_fmac_f32_e32 v106, v68, v68
	v_fma_f32 v67, v88, v62, -v96
	v_fmac_f32_e32 v106, v67, v67
	v_fma_f32 v66, v89, v61, -v96
	v_fmac_f32_e32 v106, v66, v66
	v_fma_f32 v65, v90, v60, -v96
	v_fmac_f32_e32 v106, v65, v65
	v_fma_f32 v64, v91, v59, -v96
	v_fmac_f32_e32 v106, v64, v64
	v_fma_f32 v63, v98, v58, -v96
	v_fmac_f32_e32 v106, v63, v63
	v_fma_f32 v62, v99, v57, -v96
	v_fmac_f32_e32 v106, v62, v62
	v_fma_f32 v61, v100, v56, -v96
	v_fmac_f32_e32 v106, v61, v61
	v_fma_f32 v60, v101, v55, -v96
	v_fmac_f32_e32 v106, v60, v60
	v_fma_f32 v59, v102, v49, -v96
	v_fmac_f32_e32 v106, v59, v59
	v_fma_f32 v58, v103, v48, -v96
	v_fmac_f32_e32 v106, v58, v58
	v_fma_f32 v57, v104, v45, -v96
	v_fmac_f32_e32 v106, v57, v57
	v_fma_f32 v56, v105, v44, -v96
	v_pk_fma_f32 v[44:45], v[36:37], v[42:43], v[96:97] op_sel_hi:[1,1,0] neg_lo:[0,0,1] neg_hi:[0,0,1]
	v_fmac_f32_e32 v106, v56, v56
	v_pk_mul_f32 v[36:37], v[44:45], v[44:45]
	v_pk_fma_f32 v[42:43], v[46:47], v[40:41], v[96:97] op_sel_hi:[1,1,0] neg_lo:[0,0,1] neg_hi:[0,0,1]
	v_add_f32_e32 v37, v37, v106
	v_add_f32_e32 v48, v36, v37
	v_pk_mul_f32 v[36:37], v[42:43], v[42:43]
	v_pk_fma_f32 v[40:41], v[92:93], v[38:39], v[96:97] op_sel_hi:[1,1,0] neg_lo:[0,0,1] neg_hi:[0,0,1]
	v_add_f32_e32 v37, v37, v48
	v_add_f32_e32 v46, v36, v37
	v_pk_mul_f32 v[36:37], v[40:41], v[40:41]
	v_pk_fma_f32 v[38:39], v[94:95], v[34:35], v[96:97] op_sel_hi:[1,1,0] neg_lo:[0,0,1] neg_hi:[0,0,1]
	v_add_f32_e32 v37, v37, v46
	v_add_f32_e32 v36, v36, v37
	v_pk_mul_f32 v[34:35], v[38:39], v[38:39]
	v_lshlrev_b32_e32 v105, 16, v3
	v_add_f32_e32 v35, v35, v36
	v_add_f32_e32 v34, v34, v35
	s_nop 1
	v_mov_b32_dpp v35, v34 quad_perm:[1,0,3,2] row_mask:0xf bank_mask:0xf
	v_lshl_add_u64 v[36:37], v[52:53], 0, s[4:5]
	v_and_b32_e32 v109, 0xffff0000, v3
	v_lshlrev_b32_e32 v113, 16, v2
	v_lshlrev_b32_e32 v112, 16, v30
	s_waitcnt lgkmcnt(0)
	v_add_f32_e32 v34, v34, v35
	s_nop 1
	v_mov_b32_dpp v35, v34 quad_perm:[2,3,0,1] row_mask:0xf bank_mask:0xf
	v_and_b32_e32 v3, 0xffff0000, v2
	v_and_b32_e32 v2, 0xffff0000, v30
	v_and_b32_e32 v96, 0xffff0000, v33
	s_waitcnt vmcnt(1)
	v_lshlrev_b32_e32 v53, 16, v14
	s_waitcnt lgkmcnt(0)
	v_add_f32_e32 v34, v34, v35
	v_fmamk_f32 v34, v34, 0x3c000000, v209
	v_cmp_gt_f32_e32 vcc, s82, v34
	v_mul_f32_e32 v35, 0x4b800000, v34
	v_and_b32_e32 v52, 0xffff0000, v14
	v_cndmask_b32_e32 v34, v34, v35, vcc
	v_rsq_f32_e32 v34, v34
	v_and_b32_e32 v14, 0xffff0000, v6
	v_lshlrev_b32_e32 v104, 16, v31
	v_and_b32_e32 v108, 0xffff0000, v31
	v_mul_f32_e32 v35, 0x45800000, v34
	v_cndmask_b32_e32 v55, v34, v35, vcc
	v_lshl_add_u64 v[34:35], v[50:51], 0, s[4:5]
	v_mov_b64_e32 v[46:47], v[144:145]
	v_mov_b64_e32 v[48:49], v[218:219]
	v_mul_f32_e32 v51, v97, v55
	v_add_u32_e32 v50, 0x11800, v0
	v_mul_f32_e32 v45, v45, v55
	v_mul_f32_e32 v44, v44, v55
	v_mul_f32_e32 v43, v43, v55
	v_mul_f32_e32 v42, v42, v55
	v_mul_f32_e32 v41, v41, v55
	v_mul_f32_e32 v40, v40, v55
	v_mul_f32_e32 v39, v39, v55
	v_mul_f32_e32 v38, v38, v55
	v_mov_b32_e32 v116, v112
	v_mov_b32_e32 v117, v2
	v_and_b32_e32 v97, 0xffff0000, v5
	v_mov_b32_e32 v110, v108
	v_mov_b32_e32 v111, v104
	v_mov_b32_e32 v30, v113
	v_mov_b32_e32 v31, v3
	v_pk_mul_f32 v[116:117], v[116:117], v[116:117]
	v_lshlrev_b32_e32 v101, 16, v4
	v_lshlrev_b32_e32 v100, 16, v32
	v_pk_mul_f32 v[110:111], v[110:111], v[110:111]
	v_pk_fma_f32 v[30:31], v[30:31], v[30:31], v[116:117]
	v_lshlrev_b32_e32 v130, 3, v162
	v_mov_b32_e32 v131, v1
	s_mov_b32 s4, s5
	s_mov_b32 s52, 0xf149f2ca
	s_waitcnt vmcnt(0)
; __device__ __forceinline__ unsigned cvt_pk_bf16(float lo, float hi) { unsigned r; asm volatile("v_cvt_pk_bf16_f32 %0, %1, %2" : "=v"(r) : "v"(lo), "v"(hi)); return r; }
; #define LAS __attribute__((address_space(3)))
; __device__ __forceinline__ void unpack8(const u32x4 w, float* f) { f[0] = bf_lo(w.x); f[1] = bf_hi(w.x); f[2] = bf_lo(w.y); f[3] = bf_hi(w.y); f[4] = bf_lo(w.z); f[5] = bf_hi(w.z); f[6] = bf_lo(w.w); f[7] = bf_hi(w.w); }
; __device__ __forceinline__ void p2_block(LAS unsigned char* lds, const bf16_t* __restrict__ PROJ, bf16_t* __restrict__ ATT, bf16_t* __restrict__ SGU, const float* __restrict__ qn, const float* __restrict__ kn, ...
;     ...
;         for (int c4 = 0; c4 < 4; ++c4) unpack8(sv[gi][c4], v + 8 * c4);
;     ...
;         for (int j = 0; j < 32; j += 2) { const unsigned pk = cvt_pk_bf16(v[j] * rstd * gp[j] + bp[j], v[j + 1] * rstd * gp[j + 1] + bp[j + 1]);
;             *(LAS unsigned short*)(dst + j * VN_STRIDE) = (unsigned short)(pk & 0xffffu); *(LAS unsigned short*)(dst + (j + 1) * VN_STRIDE) = (unsigned short)(pk >> 16); }
	v_fma_f32 v46, v46, v51, v48
	v_mul_f32_e32 v48, v83, v55
	v_fmac_f32_e32 v49, v47, v48
	v_add_u32_e32 v47, 0x11910, v0
	v_cvt_pk_bf16_f32 v46, v46, v49
	ds_write_b16 v50, v46
	ds_write_b16_d16_hi v47, v46
	v_mov_b64_e32 v[46:47], v[146:147]
	v_mov_b64_e32 v[48:49], v[220:221]
	v_mul_f32_e32 v50, v77, v55
	v_lshlrev_b32_e32 v51, 16, v15
	s_waitcnt vmcnt(0)
	v_fma_f32 v46, v46, v50, v48
	v_mul_f32_e32 v48, v76, v55
	v_fmac_f32_e32 v49, v47, v48
	v_add_u32_e32 v47, 0x11a20, v0
	v_cvt_pk_bf16_f32 v46, v46, v49
	ds_write_b16 v47, v46
	v_add_u32_e32 v47, 0x11b30, v0
	ds_write_b16_d16_hi v47, v46
	v_mov_b64_e32 v[46:47], v[148:149]
	v_mov_b64_e32 v[48:49], v[222:223]
	v_mul_f32_e32 v50, v75, v55
	s_waitcnt vmcnt(0)
	v_fma_f32 v46, v46, v50, v48
	v_mul_f32_e32 v48, v74, v55
	v_fmac_f32_e32 v49, v47, v48
	v_add_u32_e32 v47, 0x11c40, v0
	v_cvt_pk_bf16_f32 v46, v46, v49
	ds_write_b16 v47, v46
	v_add_u32_e32 v47, 0x11d50, v0
	ds_write_b16_d16_hi v47, v46
	v_mov_b64_e32 v[46:47], v[150:151]
	v_mov_b64_e32 v[48:49], v[224:225]
	v_mul_f32_e32 v50, v73, v55
	s_waitcnt vmcnt(0)
	v_fma_f32 v46, v46, v50, v48
	v_mul_f32_e32 v48, v72, v55
	v_fmac_f32_e32 v49, v47, v48
	v_add_u32_e32 v47, 0x11e60, v0
	v_cvt_pk_bf16_f32 v46, v46, v49
	ds_write_b16 v47, v46
	v_add_u32_e32 v47, 0x11f70, v0
	ds_write_b16_d16_hi v47, v46
	v_mov_b64_e32 v[46:47], v[152:153]
	v_mov_b64_e32 v[48:49], v[226:227]
	v_mul_f32_e32 v50, v71, v55
	s_waitcnt vmcnt(0)
	v_fma_f32 v46, v46, v50, v48
	v_mul_f32_e32 v48, v70, v55
	v_fmac_f32_e32 v49, v47, v48
	v_add_u32_e32 v47, 0x12080, v0
	v_cvt_pk_bf16_f32 v46, v46, v49
	ds_write_b16 v47, v46
	v_add_u32_e32 v47, 0x12190, v0
	ds_write_b16_d16_hi v47, v46
	v_mov_b64_e32 v[46:47], v[154:155]
	v_mov_b64_e32 v[48:49], v[228:229]
	v_mul_f32_e32 v50, v69, v55
	s_waitcnt vmcnt(0)
	v_fma_f32 v46, v46, v50, v48
	v_mul_f32_e32 v48, v68, v55
	v_fmac_f32_e32 v49, v47, v48
	v_add_u32_e32 v47, 0x122a0, v0
	v_cvt_pk_bf16_f32 v46, v46, v49
	ds_write_b16 v47, v46
	v_add_u32_e32 v47, 0x123b0, v0
	ds_write_b16_d16_hi v47, v46
	v_mov_b64_e32 v[46:47], v[156:157]
	v_mov_b64_e32 v[48:49], v[230:231]
	v_mul_f32_e32 v50, v67, v55
	s_waitcnt vmcnt(0)
	v_fma_f32 v46, v46, v50, v48
	v_mul_f32_e32 v48, v66, v55
	v_fmac_f32_e32 v49, v48, v47
	v_add_u32_e32 v47, 0x124c0, v0
	v_cvt_pk_bf16_f32 v46, v46, v49
	ds_write_b16 v47, v46
	v_add_u32_e32 v47, 0x125d0, v0
	ds_write_b16_d16_hi v47, v46
	v_mov_b64_e32 v[46:47], v[158:159]
	v_mov_b64_e32 v[48:49], v[232:233]
	v_mul_f32_e32 v50, v65, v55
	s_waitcnt vmcnt(0)
	v_fma_f32 v46, v50, v46, v48
	v_mul_f32_e32 v48, v64, v55
	v_fmac_f32_e32 v49, v48, v47
	v_add_u32_e32 v47, 0x126e0, v0
	v_cvt_pk_bf16_f32 v46, v46, v49
	ds_write_b16 v47, v46
	v_add_u32_e32 v47, 0x127f0, v0
	ds_write_b16_d16_hi v47, v46
	v_mov_b64_e32 v[46:47], v[184:185]
	v_mov_b64_e32 v[48:49], v[234:235]
	v_mul_f32_e32 v50, v63, v55
	s_waitcnt vmcnt(0)
	v_fma_f32 v46, v50, v46, v48
	v_mul_f32_e32 v48, v62, v55
	v_fmac_f32_e32 v49, v48, v47
	v_add_u32_e32 v47, 0x12900, v0
	v_cvt_pk_bf16_f32 v46, v46, v49
	ds_write_b16 v47, v46
	v_add_u32_e32 v47, 0x12a10, v0
	ds_write_b16_d16_hi v47, v46
	v_mov_b64_e32 v[46:47], v[186:187]
	v_mov_b64_e32 v[48:49], v[236:237]
	v_mul_f32_e32 v50, v61, v55
	v_lshlrev_b32_e32 v61, 16, v18
	v_and_b32_e32 v62, 0xffff0000, v18
	s_waitcnt vmcnt(0)
	v_fma_f32 v46, v50, v46, v48
	v_mul_f32_e32 v48, v60, v55
	v_fmac_f32_e32 v49, v48, v47
	v_add_u32_e32 v47, 0x12b20, v0
	v_cvt_pk_bf16_f32 v46, v46, v49
	ds_write_b16 v47, v46
	v_add_u32_e32 v47, 0x12c30, v0
	ds_write_b16_d16_hi v47, v46
	v_mov_b64_e32 v[46:47], v[188:189]
	v_mov_b64_e32 v[48:49], v[238:239]
	v_mul_f32_e32 v50, v59, v55
	v_lshlrev_b32_e32 v60, 16, v19
	v_and_b32_e32 v59, 0xffff0000, v19
	s_waitcnt vmcnt(0)
	v_fma_f32 v46, v50, v46, v48
	v_mul_f32_e32 v48, v58, v55
	v_fmac_f32_e32 v49, v48, v47
	v_add_u32_e32 v47, 0x12d40, v0
	v_cvt_pk_bf16_f32 v46, v46, v49
	ds_write_b16 v47, v46
	v_add_u32_e32 v47, 0x12e50, v0
	ds_write_b16_d16_hi v47, v46
	v_mov_b64_e32 v[46:47], v[190:191]
	v_mov_b64_e32 v[48:49], v[240:241]
	v_mul_f32_e32 v50, v57, v55
	v_lshlrev_b32_e32 v58, 16, v20
	v_and_b32_e32 v57, 0xffff0000, v20
	s_waitcnt vmcnt(0)
	v_fma_f32 v46, v50, v46, v48
	v_mul_f32_e32 v48, v56, v55
	v_fmac_f32_e32 v49, v48, v47
	v_add_u32_e32 v47, 0x12f60, v0
	v_cvt_pk_bf16_f32 v46, v46, v49
	ds_write_b16 v47, v46
	v_add_u32_e32 v47, 0x13070, v0
	ds_write_b16_d16_hi v47, v46
	v_mov_b64_e32 v[46:47], v[192:193]
	v_mov_b64_e32 v[48:49], v[242:243]
	v_and_b32_e32 v50, 0xffff0000, v15
	v_lshlrev_b32_e32 v15, 16, v6
	v_and_b32_e32 v6, 0xffff0000, v9
	v_lshlrev_b32_e32 v56, 16, v21
	v_and_b32_e32 v55, 0xffff0000, v21
	v_mul_f32_e32 v88, 0x3d372713, v6
	v_fma_f32 v88, v88, v6, 1.0
	s_waitcnt vmcnt(0)
	v_fma_f32 v45, v45, v46, v48
	v_fmac_f32_e32 v49, v44, v47
	v_cvt_pk_bf16_f32 v44, v45, v49
	v_add_u32_e32 v45, 0x13180, v0
	ds_write_b16 v45, v44
	v_add_u32_e32 v45, 0x13290, v0
	ds_write_b16_d16_hi v45, v44
	v_mov_b64_e32 v[44:45], v[194:195]
	v_mov_b64_e32 v[46:47], v[244:245]
	v_lshlrev_b32_e32 v49, 16, v16
	v_and_b32_e32 v48, 0xffff0000, v16
	s_waitcnt vmcnt(0)
	v_fma_f32 v43, v43, v44, v46
	v_fmac_f32_e32 v47, v42, v45
	v_cvt_pk_bf16_f32 v42, v43, v47
	v_add_u32_e32 v43, 0x133a0, v0
	ds_write_b16 v43, v42
	v_add_u32_e32 v43, 0x134b0, v0
	ds_write_b16_d16_hi v43, v42
	v_mov_b64_e32 v[42:43], v[196:197]
	v_mov_b64_e32 v[44:45], v[200:201]
	v_lshlrev_b32_e32 v47, 16, v17
	v_and_b32_e32 v46, 0xffff0000, v17
	v_mul_f32_e32 v17, 0x3d372713, v14
	v_fma_f32 v17, v17, v14, 1.0
	s_waitcnt vmcnt(0)
; __device__ __forceinline__ unsigned cvt_pk_bf16(float lo, float hi) { unsigned r; asm volatile("v_cvt_pk_bf16_f32 %0, %1, %2" : "=v"(r) : "v"(lo), "v"(hi)); return r; }
; __device__ __forceinline__ float gelu_f(float x) { const float y2 = 1.5957691216057308f * x * (1.0f + 0.044715f * x * x); return x * sigmoid_f(y2); }
; #define LAS __attribute__((address_space(3)))
; __device__ __forceinline__ void p2_block(LAS unsigned char* lds, const bf16_t* __restrict__ PROJ, bf16_t* __restrict__ ATT, bf16_t* __restrict__ SGU, const float* __restrict__ qn, const float* __restrict__ kn, ...
;     ...
;         for (int j = 0; j < 32; ++j) { v[j] = gelu_f(v[j]); sm += v[j]; }
;     ...
;         const float* gp = lng + gg * 128 + 32 * q4; const float* bp = lnb + gg * 128 + 32 * q4;
;         LAS unsigned char* dst = lds + (gi ? VN_OFF1 : VN_OFF0) + (32 * q4) * VN_STRIDE + sp_ * 2;
; #pragma unroll
;         for (int j = 0; j < 32; j += 2) { const unsigned pk = cvt_pk_bf16(v[j] * rstd * gp[j] + bp[j], v[j + 1] * rstd * gp[j + 1] + bp[j + 1]);
;             *(LAS unsigned short*)(dst + j * VN_STRIDE) = (unsigned short)(pk & 0xffffu); *(LAS unsigned short*)(dst + (j + 1) * VN_STRIDE) = (unsigned short)(pk >> 16); }
	v_fma_f32 v41, v41, v42, v44
	v_fmac_f32_e32 v45, v40, v43
	v_cvt_pk_bf16_f32 v40, v41, v45
	v_add_u32_e32 v41, 0x135c0, v0
	ds_write_b16 v41, v40
	v_add_u32_e32 v41, 0x136d0, v0
	ds_write_b16_d16_hi v41, v40
	v_mov_b64_e32 v[40:41], v[198:199]
	v_mov_b64_e32 v[42:43], v[202:203]
	v_lshlrev_b32_e32 v45, 16, v10
	v_and_b32_e32 v44, 0xffff0000, v10
	v_and_b32_e32 v10, 0xffff0000, v8
	s_waitcnt vmcnt(0)
	global_load_dwordx4 v[144:147], v182, s[36:37] offset:512
	global_load_dwordx4 v[148:151], v182, s[36:37] offset:528
	global_load_dwordx4 v[152:155], v182, s[36:37] offset:544
	global_load_dwordx4 v[156:159], v182, s[36:37] offset:560
	global_load_dwordx4 v[184:187], v182, s[36:37] offset:576
	global_load_dwordx4 v[188:191], v182, s[36:37] offset:592
	global_load_dwordx4 v[192:195], v182, s[36:37] offset:608
	global_load_dwordx4 v[196:199], v182, s[36:37] offset:624
	global_load_dwordx4 v[218:221], v182, s[18:19] offset:512
	global_load_dwordx4 v[222:225], v182, s[18:19] offset:528
	global_load_dwordx4 v[226:229], v182, s[18:19] offset:544
	global_load_dwordx4 v[230:233], v182, s[18:19] offset:560
	global_load_dwordx4 v[234:237], v182, s[18:19] offset:576
	global_load_dwordx4 v[238:241], v182, s[18:19] offset:592
	global_load_dwordx4 v[242:245], v182, s[18:19] offset:608
	global_load_dwordx4 v[200:203], v182, s[18:19] offset:624
	v_fma_f32 v39, v39, v40, v42
	v_fmac_f32_e32 v43, v38, v41
	v_cvt_pk_bf16_f32 v38, v39, v43
	v_add_u32_e32 v39, 0x137e0, v0
	ds_write_b16 v39, v38
	v_add_u32_e32 v39, 0x138f0, v0
	ds_write_b16_d16_hi v39, v38
	v_lshlrev_b32_e32 v41, 16, v12
	v_and_b32_e32 v40, 0xffff0000, v12
	v_lshlrev_b32_e32 v39, 16, v13
	v_and_b32_e32 v38, 0xffff0000, v13
	v_lshlrev_b32_e32 v13, 16, v7
	v_and_b32_e32 v12, 0xffff0000, v7
	v_lshlrev_b32_e32 v7, 16, v9
	v_mul_f32_e32 v9, 0x3d372713, v61
	v_lshlrev_b32_e32 v43, 16, v11
	v_and_b32_e32 v42, 0xffff0000, v11
	v_lshlrev_b32_e32 v11, 16, v8
	v_mul_f32_e32 v8, 0x3fcc422a, v61
	v_fma_f32 v9, v9, v61, 1.0
	v_mul_f32_e32 v8, v8, v9
	v_mul_f32_e32 v8, 0xbfb8aa3b, v8
	v_exp_f32_e32 v8, v8
	v_mul_f32_e32 v9, 0x3d372713, v62
	v_fma_f32 v9, v9, v62, 1.0
	v_add_f32_e32 v8, 1.0, v8
	v_rcp_f32_e32 v63, v8
	v_mul_f32_e32 v8, 0x3fcc422a, v62
	v_mul_f32_e32 v8, v8, v9
	v_mul_f32_e32 v8, 0xbfb8aa3b, v8
	v_exp_f32_e32 v8, v8
	v_mul_f32_e32 v9, 0x3d372713, v60
	v_fma_f32 v9, v9, v60, 1.0
	v_fma_f32 v16, v63, v61, 0
	v_add_f32_e32 v8, 1.0, v8
	v_rcp_f32_e32 v64, v8
	v_mul_f32_e32 v8, 0x3fcc422a, v60
	v_mul_f32_e32 v8, v8, v9
	v_mul_f32_e32 v8, 0xbfb8aa3b, v8
	v_exp_f32_e32 v8, v8
	v_mul_f32_e32 v9, 0x3d372713, v59
	v_fma_f32 v9, v9, v59, 1.0
	v_fmac_f32_e32 v16, v64, v62
	v_add_f32_e32 v8, 1.0, v8
	v_rcp_f32_e32 v65, v8
	v_mul_f32_e32 v8, 0x3fcc422a, v59
	v_mul_f32_e32 v8, v8, v9
	v_mul_f32_e32 v8, 0xbfb8aa3b, v8
	v_exp_f32_e32 v8, v8
	v_mul_f32_e32 v9, 0x3d372713, v58
	v_fma_f32 v9, v9, v58, 1.0
	v_fmac_f32_e32 v16, v65, v60
	v_add_f32_e32 v8, 1.0, v8
	v_rcp_f32_e32 v66, v8
	v_mul_f32_e32 v8, 0x3fcc422a, v58
	v_mul_f32_e32 v8, v8, v9
	v_mul_f32_e32 v8, 0xbfb8aa3b, v8
	v_exp_f32_e32 v8, v8
	v_mul_f32_e32 v9, 0x3d372713, v57
	v_fma_f32 v9, v9, v57, 1.0
	v_fmac_f32_e32 v16, v66, v59
	v_add_f32_e32 v8, 1.0, v8
	v_rcp_f32_e32 v67, v8
	v_mul_f32_e32 v8, 0x3fcc422a, v57
	v_mul_f32_e32 v8, v8, v9
	v_mul_f32_e32 v8, 0xbfb8aa3b, v8
	v_exp_f32_e32 v8, v8
	v_mul_f32_e32 v9, 0x3d372713, v56
	v_fma_f32 v9, v9, v56, 1.0
	v_fmac_f32_e32 v16, v67, v58
	v_add_f32_e32 v8, 1.0, v8
	v_rcp_f32_e32 v68, v8
	v_mul_f32_e32 v8, 0x3fcc422a, v56
	v_mul_f32_e32 v8, v8, v9
	v_mul_f32_e32 v8, 0xbfb8aa3b, v8
	v_exp_f32_e32 v8, v8
	v_mul_f32_e32 v9, 0x3d372713, v55
	v_fma_f32 v9, v9, v55, 1.0
	v_fmac_f32_e32 v16, v68, v57
	v_add_f32_e32 v8, 1.0, v8
	v_rcp_f32_e32 v69, v8
	v_mul_f32_e32 v8, 0x3fcc422a, v55
	v_mul_f32_e32 v8, v8, v9
	v_mul_f32_e32 v8, 0xbfb8aa3b, v8
	v_exp_f32_e32 v8, v8
	v_mul_f32_e32 v9, 0x3d372713, v53
	v_fma_f32 v9, v9, v53, 1.0
	v_fmac_f32_e32 v16, v69, v56
	v_add_f32_e32 v8, 1.0, v8
	v_rcp_f32_e32 v70, v8
	v_mul_f32_e32 v8, 0x3fcc422a, v53
	v_mul_f32_e32 v8, v8, v9
	v_mul_f32_e32 v8, 0xbfb8aa3b, v8
	v_exp_f32_e32 v8, v8
	v_mul_f32_e32 v9, 0x3d372713, v52
	v_fma_f32 v9, v9, v52, 1.0
	v_fmac_f32_e32 v16, v70, v55
	v_add_f32_e32 v8, 1.0, v8
	v_rcp_f32_e32 v71, v8
	v_mul_f32_e32 v8, 0x3fcc422a, v52
	v_mul_f32_e32 v8, v8, v9
	v_mul_f32_e32 v8, 0xbfb8aa3b, v8
	v_exp_f32_e32 v8, v8
	v_mul_f32_e32 v9, 0x3d372713, v51
	v_fma_f32 v9, v9, v51, 1.0
	v_fmac_f32_e32 v16, v71, v53
	v_add_f32_e32 v8, 1.0, v8
	v_rcp_f32_e32 v72, v8
	v_mul_f32_e32 v8, 0x3fcc422a, v51
	v_mul_f32_e32 v8, v8, v9
	v_mul_f32_e32 v8, 0xbfb8aa3b, v8
	v_exp_f32_e32 v8, v8
	v_mul_f32_e32 v9, 0x3d372713, v50
	v_fma_f32 v9, v9, v50, 1.0
	v_fmac_f32_e32 v16, v72, v52
	v_add_f32_e32 v8, 1.0, v8
	v_rcp_f32_e32 v73, v8
	v_mul_f32_e32 v8, 0x3fcc422a, v50
	v_mul_f32_e32 v8, v8, v9
	v_mul_f32_e32 v8, 0xbfb8aa3b, v8
	v_exp_f32_e32 v8, v8
	v_mul_f32_e32 v9, 0x3d372713, v49
	v_fma_f32 v9, v9, v49, 1.0
	v_fmac_f32_e32 v16, v73, v51
	v_add_f32_e32 v8, 1.0, v8
	v_rcp_f32_e32 v74, v8
	v_mul_f32_e32 v8, 0x3fcc422a, v49
	v_mul_f32_e32 v8, v8, v9
	v_mul_f32_e32 v8, 0xbfb8aa3b, v8
	v_exp_f32_e32 v8, v8
	v_mul_f32_e32 v9, 0x3d372713, v48
	v_fma_f32 v9, v9, v48, 1.0
	v_fmac_f32_e32 v16, v74, v50
	v_add_f32_e32 v8, 1.0, v8
	v_rcp_f32_e32 v75, v8
	v_mul_f32_e32 v8, 0x3fcc422a, v48
	v_mul_f32_e32 v8, v8, v9
	v_mul_f32_e32 v8, 0xbfb8aa3b, v8
	v_exp_f32_e32 v8, v8
	v_mul_f32_e32 v9, 0x3d372713, v47
	v_fma_f32 v9, v9, v47, 1.0
	v_fmac_f32_e32 v16, v75, v49
	v_add_f32_e32 v8, 1.0, v8
	v_rcp_f32_e32 v76, v8
	v_mul_f32_e32 v8, 0x3fcc422a, v47
	v_mul_f32_e32 v8, v8, v9
	v_mul_f32_e32 v8, 0xbfb8aa3b, v8
; __device__ __forceinline__ float gelu_f(float x) { const float y2 = 1.5957691216057308f * x * (1.0f + 0.044715f * x * x); return x * sigmoid_f(y2); }
; __device__ __forceinline__ void p2_block(LAS unsigned char* lds, const bf16_t* __restrict__ PROJ, bf16_t* __restrict__ ATT, bf16_t* __restrict__ SGU, const float* __restrict__ qn, const float* __restrict__ kn, ...
;     ...
;         for (int j = 0; j < 32; ++j) { v[j] = gelu_f(v[j]); sm += v[j]; }
;         sm += __shfl_xor(sm, 1); sm += __shfl_xor(sm, 2);
	v_exp_f32_e32 v8, v8
	v_mul_f32_e32 v9, 0x3d372713, v46
	v_fma_f32 v9, v9, v46, 1.0
	v_fmac_f32_e32 v16, v76, v48
	v_add_f32_e32 v8, 1.0, v8
	v_rcp_f32_e32 v77, v8
	v_mul_f32_e32 v8, 0x3fcc422a, v46
	v_mul_f32_e32 v8, v8, v9
	v_mul_f32_e32 v8, 0xbfb8aa3b, v8
	v_exp_f32_e32 v8, v8
	v_mul_f32_e32 v9, 0x3d372713, v45
	v_fma_f32 v9, v9, v45, 1.0
	v_fmac_f32_e32 v16, v77, v47
	v_add_f32_e32 v8, 1.0, v8
	v_rcp_f32_e32 v78, v8
	v_mul_f32_e32 v8, 0x3fcc422a, v45
	v_mul_f32_e32 v8, v8, v9
	v_mul_f32_e32 v8, 0xbfb8aa3b, v8
	v_exp_f32_e32 v8, v8
	v_mul_f32_e32 v9, 0x3d372713, v44
	v_fma_f32 v9, v9, v44, 1.0
	v_fmac_f32_e32 v16, v78, v46
	v_add_f32_e32 v8, 1.0, v8
	v_rcp_f32_e32 v79, v8
	v_mul_f32_e32 v8, 0x3fcc422a, v44
	v_mul_f32_e32 v8, v8, v9
	v_mul_f32_e32 v8, 0xbfb8aa3b, v8
	v_exp_f32_e32 v8, v8
	v_mul_f32_e32 v9, 0x3d372713, v43
	v_fma_f32 v9, v9, v43, 1.0
	v_fmac_f32_e32 v16, v79, v45
	v_add_f32_e32 v8, 1.0, v8
	v_rcp_f32_e32 v80, v8
	v_mul_f32_e32 v8, 0x3fcc422a, v43
	v_mul_f32_e32 v8, v8, v9
	v_mul_f32_e32 v8, 0xbfb8aa3b, v8
	v_exp_f32_e32 v8, v8
	v_mul_f32_e32 v9, 0x3d372713, v42
	v_fma_f32 v9, v9, v42, 1.0
	v_fmac_f32_e32 v16, v80, v44
	v_add_f32_e32 v8, 1.0, v8
	v_rcp_f32_e32 v81, v8
	v_mul_f32_e32 v8, 0x3fcc422a, v42
	v_mul_f32_e32 v8, v8, v9
	v_mul_f32_e32 v8, 0xbfb8aa3b, v8
	v_exp_f32_e32 v8, v8
	v_mul_f32_e32 v9, 0x3d372713, v41
	v_fma_f32 v9, v9, v41, 1.0
	v_fmac_f32_e32 v16, v81, v43
	v_add_f32_e32 v8, 1.0, v8
	v_rcp_f32_e32 v82, v8
	v_mul_f32_e32 v8, 0x3fcc422a, v41
	v_mul_f32_e32 v8, v8, v9
	v_mul_f32_e32 v8, 0xbfb8aa3b, v8
	v_exp_f32_e32 v8, v8
	v_mul_f32_e32 v9, 0x3d372713, v40
	v_fma_f32 v9, v9, v40, 1.0
	v_fmac_f32_e32 v16, v82, v42
	v_add_f32_e32 v8, 1.0, v8
	v_rcp_f32_e32 v83, v8
	v_mul_f32_e32 v8, 0x3fcc422a, v40
	v_mul_f32_e32 v8, v8, v9
	v_mul_f32_e32 v8, 0xbfb8aa3b, v8
	v_exp_f32_e32 v8, v8
	v_mul_f32_e32 v9, 0x3d372713, v39
	v_fma_f32 v9, v9, v39, 1.0
	v_fmac_f32_e32 v16, v83, v41
	v_add_f32_e32 v8, 1.0, v8
	v_rcp_f32_e32 v84, v8
	v_mul_f32_e32 v8, 0x3fcc422a, v39
	v_mul_f32_e32 v8, v8, v9
	v_mul_f32_e32 v8, 0xbfb8aa3b, v8
	v_exp_f32_e32 v8, v8
	v_mul_f32_e32 v9, 0x3d372713, v38
	v_fma_f32 v9, v9, v38, 1.0
	v_fmac_f32_e32 v16, v84, v40
	v_add_f32_e32 v8, 1.0, v8
	v_rcp_f32_e32 v85, v8
	v_mul_f32_e32 v8, 0x3fcc422a, v38
	v_mul_f32_e32 v8, v8, v9
	v_mul_f32_e32 v8, 0xbfb8aa3b, v8
	v_exp_f32_e32 v8, v8
	v_mul_f32_e32 v9, 0x3d372713, v15
	v_fma_f32 v9, v9, v15, 1.0
	v_fmac_f32_e32 v16, v85, v39
	v_add_f32_e32 v8, 1.0, v8
	v_rcp_f32_e32 v86, v8
	v_mul_f32_e32 v8, 0x3fcc422a, v15
	v_mul_f32_e32 v8, v8, v9
	v_mul_f32_e32 v8, 0xbfb8aa3b, v8
	v_exp_f32_e32 v8, v8
	v_fmac_f32_e32 v16, v86, v38
	v_add_f32_e32 v8, 1.0, v8
	v_rcp_f32_e32 v9, v8
	v_mul_f32_e32 v8, 0x3fcc422a, v14
	v_mul_f32_e32 v8, v8, v17
	v_mul_f32_e32 v8, 0xbfb8aa3b, v8
	v_exp_f32_e32 v8, v8
	v_mul_f32_e32 v17, 0x3d372713, v13
	v_fma_f32 v17, v17, v13, 1.0
	v_add_f32_e32 v8, 1.0, v8
	v_rcp_f32_e32 v8, v8
	s_nop 0
	v_pk_mul_f32 v[18:19], v[8:9], v[14:15]
	s_nop 0
	v_add_f32_e32 v16, v19, v16
	v_add_f32_e32 v20, v18, v16
	v_mul_f32_e32 v16, 0x3fcc422a, v13
	v_mul_f32_e32 v16, v16, v17
	v_mul_f32_e32 v16, 0xbfb8aa3b, v16
	v_exp_f32_e32 v16, v16
	v_mul_f32_e32 v18, 0x3d372713, v12
	v_fma_f32 v18, v18, v12, 1.0
	v_add_f32_e32 v16, 1.0, v16
	v_rcp_f32_e32 v17, v16
	v_mul_f32_e32 v16, 0x3fcc422a, v12
	v_mul_f32_e32 v16, v16, v18
	v_mul_f32_e32 v16, 0xbfb8aa3b, v16
	v_exp_f32_e32 v16, v16
	s_nop 0
	v_add_f32_e32 v16, 1.0, v16
	v_rcp_f32_e32 v16, v16
	s_nop 0
	v_pk_mul_f32 v[18:19], v[16:17], v[12:13]
	s_nop 0
	v_add_f32_e32 v19, v19, v20
	v_add_f32_e32 v87, v18, v19
	v_mul_f32_e32 v19, 0x3d372713, v11
	v_mul_f32_e32 v18, 0x3fcc422a, v11
	v_fma_f32 v19, v19, v11, 1.0
	v_mul_f32_e32 v18, v18, v19
	v_mul_f32_e32 v18, 0xbfb8aa3b, v18
	v_exp_f32_e32 v18, v18
	v_mul_f32_e32 v20, 0x3d372713, v10
	v_fma_f32 v20, v20, v10, 1.0
	v_add_f32_e32 v18, 1.0, v18
	v_rcp_f32_e32 v19, v18
	v_mul_f32_e32 v18, 0x3fcc422a, v10
	v_mul_f32_e32 v18, v18, v20
	v_mul_f32_e32 v18, 0xbfb8aa3b, v18
	v_exp_f32_e32 v18, v18
	s_nop 0
	v_add_f32_e32 v18, 1.0, v18
	v_rcp_f32_e32 v18, v18
	s_nop 0
	v_pk_mul_f32 v[20:21], v[18:19], v[10:11]
	s_nop 0
	v_add_f32_e32 v21, v21, v87
	v_add_f32_e32 v87, v20, v21
	v_mul_f32_e32 v21, 0x3d372713, v7
	v_mul_f32_e32 v20, 0x3fcc422a, v7
	v_fma_f32 v21, v21, v7, 1.0
	v_mul_f32_e32 v20, v20, v21
	v_mul_f32_e32 v20, 0xbfb8aa3b, v20
	v_exp_f32_e32 v20, v20
	s_nop 0
	v_add_f32_e32 v20, 1.0, v20
	v_rcp_f32_e32 v21, v20
	v_mul_f32_e32 v20, 0x3fcc422a, v6
	v_mul_f32_e32 v20, v20, v88
	v_mul_f32_e32 v20, 0xbfb8aa3b, v20
	v_exp_f32_e32 v20, v20
	s_nop 0
	v_add_f32_e32 v20, 1.0, v20
	v_rcp_f32_e32 v20, v20
	s_nop 0
	v_pk_mul_f32 v[88:89], v[20:21], v[6:7]
	s_nop 0
	v_add_f32_e32 v87, v89, v87
	v_add_f32_e32 v87, v88, v87
	s_nop 1
	v_mov_b32_dpp v88, v87 quad_perm:[1,0,3,2] row_mask:0xf bank_mask:0xf
	s_waitcnt lgkmcnt(0)
	v_add_f32_e32 v87, v87, v88
	s_nop 1
	v_mov_b32_dpp v88, v87 quad_perm:[2,3,0,1] row_mask:0xf bank_mask:0xf
	s_waitcnt lgkmcnt(0)
; __device__ __forceinline__ unsigned cvt_pk_bf16(float lo, float hi) { unsigned r; asm volatile("v_cvt_pk_bf16_f32 %0, %1, %2" : "=v"(r) : "v"(lo), "v"(hi)); return r; }
; #define LAS __attribute__((address_space(3)))
; __device__ __forceinline__ void p2_block(LAS unsigned char* lds, const bf16_t* __restrict__ PROJ, bf16_t* __restrict__ ATT, bf16_t* __restrict__ SGU, const float* __restrict__ qn, const float* __restrict__ kn, ...
;     ...
;         const float mu = sm * (1.0f / 128.0f); float q = 0.f;
; #pragma unroll
;         for (int j = 0; j < 32; ++j) { v[j] -= mu; q += v[j] * v[j]; }
;         q += __shfl_xor(q, 1); q += __shfl_xor(q, 2);
;         const float rstd = rsqrtf(q * (1.0f / 128.0f) + pg8::EPS);
;         const float* gp = lng + gg * 128 + 32 * q4; const float* bp = lnb + gg * 128 + 32 * q4;
;         LAS unsigned char* dst = lds + (gi ? VN_OFF1 : VN_OFF0) + (32 * q4) * VN_STRIDE + sp_ * 2;
; #pragma unroll
;         for (int j = 0; j < 32; j += 2) { const unsigned pk = cvt_pk_bf16(v[j] * rstd * gp[j] + bp[j], v[j + 1] * rstd * gp[j + 1] + bp[j + 1]);
;             *(LAS unsigned short*)(dst + j * VN_STRIDE) = (unsigned short)(pk & 0xffffu); *(LAS unsigned short*)(dst + (j + 1) * VN_STRIDE) = (unsigned short)(pk >> 16); }
	v_add_f32_e32 v87, v87, v88
	v_mul_f32_e32 v88, 0x3c000000, v87
	v_fma_f32 v63, v63, v61, -v88
	v_fma_f32 v61, v64, v62, -v88
	v_mul_f32_e32 v62, v61, v61
	v_fmac_f32_e32 v62, v63, v63
	v_fma_f32 v60, v65, v60, -v88
	v_fmac_f32_e32 v62, v60, v60
	v_fma_f32 v59, v66, v59, -v88
	v_fmac_f32_e32 v62, v59, v59
	v_fma_f32 v58, v67, v58, -v88
	v_fmac_f32_e32 v62, v58, v58
	v_fma_f32 v57, v68, v57, -v88
	v_fmac_f32_e32 v62, v57, v57
	v_fma_f32 v56, v69, v56, -v88
	v_fmac_f32_e32 v62, v56, v56
	v_fma_f32 v55, v70, v55, -v88
	v_fmac_f32_e32 v62, v55, v55
	v_fma_f32 v53, v71, v53, -v88
	v_fmac_f32_e32 v62, v53, v53
	v_fma_f32 v52, v72, v52, -v88
	v_fmac_f32_e32 v62, v52, v52
	v_fma_f32 v51, v73, v51, -v88
	v_fmac_f32_e32 v62, v51, v51
	v_fma_f32 v50, v74, v50, -v88
	v_fmac_f32_e32 v62, v50, v50
	v_fma_f32 v49, v75, v49, -v88
	v_fmac_f32_e32 v62, v49, v49
	v_fma_f32 v48, v76, v48, -v88
	v_fmac_f32_e32 v62, v48, v48
	v_fma_f32 v47, v77, v47, -v88
	v_fmac_f32_e32 v62, v47, v47
	v_fma_f32 v46, v78, v46, -v88
	v_fmac_f32_e32 v62, v46, v46
	v_fma_f32 v45, v79, v45, -v88
	v_fmac_f32_e32 v62, v45, v45
	v_fma_f32 v44, v80, v44, -v88
	v_fmac_f32_e32 v62, v44, v44
	v_fma_f32 v43, v81, v43, -v88
	v_fmac_f32_e32 v62, v43, v43
	v_fma_f32 v42, v82, v42, -v88
	v_fmac_f32_e32 v62, v42, v42
	v_fma_f32 v41, v83, v41, -v88
	v_fmac_f32_e32 v62, v41, v41
	v_fma_f32 v40, v84, v40, -v88
	v_fmac_f32_e32 v62, v40, v40
	v_fma_f32 v39, v85, v39, -v88
	v_fmac_f32_e32 v62, v39, v39
	v_fma_f32 v38, v86, v38, -v88
	v_pk_fma_f32 v[14:15], v[8:9], v[14:15], v[88:89] op_sel_hi:[1,1,0] neg_lo:[0,0,1] neg_hi:[0,0,1]
	v_fmac_f32_e32 v62, v38, v38
	v_pk_mul_f32 v[8:9], v[14:15], v[14:15]
	v_pk_fma_f32 v[12:13], v[16:17], v[12:13], v[88:89] op_sel_hi:[1,1,0] neg_lo:[0,0,1] neg_hi:[0,0,1]
	v_add_f32_e32 v9, v9, v62
	v_add_f32_e32 v62, v8, v9
	v_pk_mul_f32 v[8:9], v[12:13], v[12:13]
	v_pk_fma_f32 v[6:7], v[20:21], v[6:7], v[88:89] op_sel_hi:[1,1,0] neg_lo:[0,0,1] neg_hi:[0,0,1]
	v_add_f32_e32 v9, v9, v62
	v_add_f32_e32 v16, v8, v9
	v_pk_fma_f32 v[8:9], v[18:19], v[10:11], v[88:89] op_sel_hi:[1,1,0] neg_lo:[0,0,1] neg_hi:[0,0,1]
	v_add_u32_e32 v19, 0x1a000, v0
	v_pk_mul_f32 v[10:11], v[8:9], v[8:9]
	v_lshlrev_b32_e32 v78, 16, v33
	v_add_f32_e32 v11, v11, v16
	v_add_f32_e32 v16, v10, v11
	v_pk_mul_f32 v[10:11], v[6:7], v[6:7]
	v_lshlrev_b32_e32 v79, 16, v5
	v_add_f32_e32 v11, v11, v16
	v_add_f32_e32 v10, v10, v11
	s_nop 1
	v_mov_b32_dpp v11, v10 quad_perm:[1,0,3,2] row_mask:0xf bank_mask:0xf
	v_and_b32_e32 v5, 0xffff0000, v4
	v_and_b32_e32 v4, 0xffff0000, v32
	v_mov_b32_e32 v32, v5
	v_mov_b32_e32 v33, v101
	s_waitcnt lgkmcnt(0)
	v_add_f32_e32 v10, v10, v11
	s_nop 1
	v_mov_b32_dpp v11, v10 quad_perm:[2,3,0,1] row_mask:0xf bank_mask:0xf
	v_mov_b32_e32 v54, v96
	v_add_u32_e32 v81, 0, v132
	v_lshlrev_b32_e32 v73, 2, v162
	v_sub_u32_e32 v74, v81, v130
	s_waitcnt lgkmcnt(0)
	v_add_f32_e32 v10, v10, v11
	v_fmamk_f32 v10, v10, 0x3c000000, v209
	v_cmp_gt_f32_e32 vcc, s82, v10
	v_mul_f32_e32 v11, 0x4b800000, v10
	v_or_b32_e32 v71, 2, v130
	v_cndmask_b32_e32 v10, v10, v11, vcc
	v_rsq_f32_e32 v10, v10
	v_or_b32_e32 v70, 3, v130
	v_or_b32_e32 v72, 4, v130
	v_mul_f32_e32 v11, 0x45800000, v10
	v_cndmask_b32_e32 v18, v10, v11, vcc
	s_waitcnt vmcnt(0)
	v_mov_b64_e32 v[10:11], v[144:145]
	v_mov_b64_e32 v[16:17], v[218:219]
	v_mul_f32_e32 v20, v63, v18
	v_mul_f32_e32 v15, v15, v18
	v_mul_f32_e32 v14, v14, v18
	v_mul_f32_e32 v13, v13, v18
	v_mul_f32_e32 v12, v12, v18
	v_mul_f32_e32 v9, v9, v18
	v_mul_f32_e32 v8, v8, v18
	v_mul_f32_e32 v7, v7, v18
	v_mul_f32_e32 v6, v6, v18
	s_waitcnt vmcnt(0)
	v_fma_f32 v10, v10, v20, v16
	v_mul_f32_e32 v16, v61, v18
	v_fmac_f32_e32 v17, v11, v16
	v_add_u32_e32 v11, 0x1a110, v0
	v_cvt_pk_bf16_f32 v10, v10, v17
	ds_write_b16 v19, v10
	ds_write_b16_d16_hi v11, v10
	v_mov_b64_e32 v[10:11], v[146:147]
	v_mov_b64_e32 v[16:17], v[220:221]
	v_mul_f32_e32 v19, v60, v18
	s_waitcnt vmcnt(0)
	v_fma_f32 v10, v10, v19, v16
	v_mul_f32_e32 v16, v59, v18
	v_fmac_f32_e32 v17, v11, v16
	v_add_u32_e32 v11, 0x1a220, v0
	v_cvt_pk_bf16_f32 v10, v10, v17
	ds_write_b16 v11, v10
	v_add_u32_e32 v11, 0x1a330, v0
	ds_write_b16_d16_hi v11, v10
	v_mov_b64_e32 v[10:11], v[148:149]
	v_mov_b64_e32 v[16:17], v[222:223]
	v_mul_f32_e32 v19, v58, v18
	s_waitcnt vmcnt(0)
	v_fma_f32 v10, v10, v19, v16
	v_mul_f32_e32 v16, v57, v18
	v_fmac_f32_e32 v17, v11, v16
	v_add_u32_e32 v11, 0x1a440, v0
	v_cvt_pk_bf16_f32 v10, v10, v17
	ds_write_b16 v11, v10
	v_add_u32_e32 v11, 0x1a550, v0
	ds_write_b16_d16_hi v11, v10
	v_mov_b64_e32 v[10:11], v[150:151]
	v_mov_b64_e32 v[16:17], v[224:225]
	v_mul_f32_e32 v19, v56, v18
	v_mov_b32_e32 v56, v109
	v_mov_b32_e32 v57, v105
	v_pk_fma_f32 v[110:111], v[56:57], v[56:57], v[110:111]
	s_waitcnt vmcnt(0)
	v_fma_f32 v10, v10, v19, v16
	v_mul_f32_e32 v16, v55, v18
	v_fmac_f32_e32 v17, v11, v16
	v_add_u32_e32 v11, 0x1a660, v0
	v_cvt_pk_bf16_f32 v10, v10, v17
	ds_write_b16 v11, v10
	v_add_u32_e32 v11, 0x1a770, v0
	ds_write_b16_d16_hi v11, v10
	v_mov_b64_e32 v[10:11], v[152:153]
	v_mov_b64_e32 v[16:17], v[226:227]
	v_mul_f32_e32 v19, v53, v18
	v_mov_b32_e32 v55, v78
	v_pk_mul_f32 v[54:55], v[54:55], v[54:55]
	s_waitcnt vmcnt(0)
	v_fma_f32 v10, v10, v19, v16
	v_mul_f32_e32 v16, v52, v18
	v_fmac_f32_e32 v17, v11, v16
	v_add_u32_e32 v11, 0x1a880, v0
	v_cvt_pk_bf16_f32 v10, v10, v17
	ds_write_b16 v11, v10
	v_add_u32_e32 v11, 0x1a990, v0
	ds_write_b16_d16_hi v11, v10
	v_mov_b64_e32 v[10:11], v[154:155]
	v_mov_b64_e32 v[16:17], v[228:229]
	v_mul_f32_e32 v19, v51, v18
	s_waitcnt vmcnt(0)
; __device__ __forceinline__ unsigned cvt_pk_bf16(float lo, float hi) { unsigned r; asm volatile("v_cvt_pk_bf16_f32 %0, %1, %2" : "=v"(r) : "v"(lo), "v"(hi)); return r; }
; #define LAS __attribute__((address_space(3)))
; __device__ __forceinline__ void p2_block(LAS unsigned char* lds, const bf16_t* __restrict__ PROJ, bf16_t* __restrict__ ATT, bf16_t* __restrict__ SGU, const float* __restrict__ qn, const float* __restrict__ kn, ...
;     ...
;         for (int j = 0; j < 32; j += 2) { const unsigned pk = cvt_pk_bf16(v[j] * rstd * gp[j] + bp[j], v[j + 1] * rstd * gp[j + 1] + bp[j + 1]);
;             *(LAS unsigned short*)(dst + j * VN_STRIDE) = (unsigned short)(pk & 0xffffu); *(LAS unsigned short*)(dst + (j + 1) * VN_STRIDE) = (unsigned short)(pk >> 16); }
;     }
;     __syncthreads();
; #pragma unroll
;     for (int c = 2; c < 4; ++c) { const bf16_t* qp = PROJ + ((size_t)b * pg8::SEQ + n * 128 + rbase + 16 * c + fr) * pg8::IN_W + hq * 64 + 8 * fq; qa[c] = *(const u32x4*)qp; qb[c] = *(const u32x4*)(qp + 32); }
;     const float sink = sinks[hq];
;     ...
;             const float* cp = COS + pos * 32 + 8 * fq; const float* sp = SIN + pos * 32 + 8 * fq;
;             float o1[8], o2[8];
; #pragma unroll
;             for (int j = 0; j < 8; ++j) { const float a1 = x1[j] * rinv * qn[8 * fq + j], a2 = x2[j] * rinv * qn[32 + 8 * fq + j], cc = cp[j], sn = sp[j]; o1[j] = a1 * cc - a2 * sn; o2[j] = a2 * cc + a1 * sn; }
	v_fma_f32 v10, v10, v19, v16
	v_mul_f32_e32 v16, v50, v18
	v_fmac_f32_e32 v17, v11, v16
	v_add_u32_e32 v11, 0x1aaa0, v0
	v_cvt_pk_bf16_f32 v10, v10, v17
	ds_write_b16 v11, v10
	v_add_u32_e32 v11, 0x1abb0, v0
	ds_write_b16_d16_hi v11, v10
	v_mov_b64_e32 v[10:11], v[156:157]
	v_mov_b64_e32 v[16:17], v[230:231]
	v_mul_f32_e32 v19, v49, v18
	s_waitcnt vmcnt(0)
	v_fma_f32 v10, v10, v19, v16
	v_mul_f32_e32 v16, v48, v18
	v_fmac_f32_e32 v17, v16, v11
	v_add_u32_e32 v11, 0x1acc0, v0
	v_cvt_pk_bf16_f32 v10, v10, v17
	ds_write_b16 v11, v10
	v_add_u32_e32 v11, 0x1add0, v0
	ds_write_b16_d16_hi v11, v10
	v_mov_b64_e32 v[10:11], v[158:159]
	v_mov_b64_e32 v[16:17], v[232:233]
	v_mul_f32_e32 v19, v47, v18
	s_waitcnt vmcnt(0)
	v_fma_f32 v10, v19, v10, v16
	v_mul_f32_e32 v16, v46, v18
	v_fmac_f32_e32 v17, v16, v11
	v_add_u32_e32 v11, 0x1aee0, v0
	v_cvt_pk_bf16_f32 v10, v10, v17
	ds_write_b16 v11, v10
	v_add_u32_e32 v11, 0x1aff0, v0
	ds_write_b16_d16_hi v11, v10
	v_mov_b64_e32 v[10:11], v[184:185]
	v_mov_b64_e32 v[16:17], v[234:235]
	v_mul_f32_e32 v19, v45, v18
	s_waitcnt vmcnt(0)
	v_fma_f32 v10, v19, v10, v16
	v_mul_f32_e32 v16, v44, v18
	v_fmac_f32_e32 v17, v16, v11
	v_add_u32_e32 v11, 0x1b100, v0
	v_cvt_pk_bf16_f32 v10, v10, v17
	ds_write_b16 v11, v10
	v_add_u32_e32 v11, 0x1b210, v0
	ds_write_b16_d16_hi v11, v10
	v_mov_b64_e32 v[10:11], v[186:187]
	v_mov_b64_e32 v[16:17], v[236:237]
	v_mul_f32_e32 v19, v43, v18
	v_or_b32_e32 v44, s17, v161
	s_waitcnt vmcnt(0)
	v_fma_f32 v10, v19, v10, v16
	v_mul_f32_e32 v16, v42, v18
	v_fmac_f32_e32 v17, v16, v11
	v_add_u32_e32 v11, 0x1b320, v0
	v_cvt_pk_bf16_f32 v10, v10, v17
	ds_write_b16 v11, v10
	v_add_u32_e32 v11, 0x1b430, v0
	ds_write_b16_d16_hi v11, v10
	v_mov_b64_e32 v[10:11], v[188:189]
	v_mov_b64_e32 v[16:17], v[238:239]
	v_mul_f32_e32 v19, v41, v18
	s_waitcnt vmcnt(0)
	v_fma_f32 v10, v19, v10, v16
	v_mul_f32_e32 v16, v40, v18
	v_fmac_f32_e32 v17, v16, v11
	v_add_u32_e32 v11, 0x1b540, v0
	v_cvt_pk_bf16_f32 v10, v10, v17
	ds_write_b16 v11, v10
	v_add_u32_e32 v11, 0x1b650, v0
	ds_write_b16_d16_hi v11, v10
	v_mov_b64_e32 v[10:11], v[190:191]
	v_mov_b64_e32 v[16:17], v[240:241]
	v_mul_f32_e32 v19, v39, v18
	s_waitcnt vmcnt(0)
	v_fma_f32 v10, v19, v10, v16
	v_mul_f32_e32 v16, v38, v18
	v_fmac_f32_e32 v17, v16, v11
	v_add_u32_e32 v11, 0x1b760, v0
	v_cvt_pk_bf16_f32 v10, v10, v17
	ds_write_b16 v11, v10
	v_add_u32_e32 v11, 0x1b870, v0
	ds_write_b16_d16_hi v11, v10
	v_mov_b64_e32 v[10:11], v[192:193]
	v_mov_b64_e32 v[16:17], v[242:243]
	s_waitcnt vmcnt(0)
	v_fma_f32 v10, v15, v10, v16
	v_fmac_f32_e32 v17, v14, v11
	v_add_u32_e32 v11, 0x1b980, v0
	v_cvt_pk_bf16_f32 v10, v10, v17
	ds_write_b16 v11, v10
	v_add_u32_e32 v11, 0x1ba90, v0
	ds_write_b16_d16_hi v11, v10
	v_mov_b64_e32 v[10:11], v[194:195]
	v_mov_b64_e32 v[14:15], v[244:245]
	s_waitcnt vmcnt(0)
	v_fma_f32 v10, v13, v10, v14
	v_fmac_f32_e32 v15, v12, v11
	v_add_u32_e32 v11, 0x1bba0, v0
	v_cvt_pk_bf16_f32 v10, v10, v15
	ds_write_b16 v11, v10
	v_add_u32_e32 v11, 0x1bcb0, v0
	ds_write_b16_d16_hi v11, v10
	v_mov_b64_e32 v[10:11], v[196:197]
	v_mov_b64_e32 v[12:13], v[200:201]
	v_lshlrev_b32_e32 v14, 7, v44
	v_mov_b32_e32 v15, v1
	v_or_b32_e32 v44, s48, v44
	s_waitcnt vmcnt(0)
	v_fma_f32 v9, v9, v10, v12
	v_fmac_f32_e32 v13, v8, v11
	v_cvt_pk_bf16_f32 v8, v9, v13
	v_add_u32_e32 v9, 0x1bdc0, v0
	ds_write_b16 v9, v8
	v_add_u32_e32 v9, 0x1bed0, v0
	ds_write_b16_d16_hi v9, v8
	v_mov_b64_e32 v[8:9], v[198:199]
	v_mov_b64_e32 v[10:11], v[202:203]
	s_waitcnt vmcnt(0)
	v_fma_f32 v7, v7, v8, v10
	v_fmac_f32_e32 v11, v6, v9
	v_cvt_pk_bf16_f32 v6, v7, v11
	v_add_u32_e32 v7, 0x1bfe0, v0
	v_add_u32_e32 v0, 0x1c0f0, v0
	ds_write_b16_d16_hi v0, v6
	v_or_b32_e32 v0, 32, v163
	ds_write_b16 v7, v6
	v_mad_u64_u32 v[6:7], s[28:29], v0, s83, v[134:135]
	v_mad_i32_i24 v7, s49, v212, v7
	v_or_b32_e32 v0, 48, v163
	v_readfirstlane_b32 s16, v204
	v_and_b32_e32 v43, 15, v204
	v_bfe_u32 v44, v204, 4, 2
	s_and_b32 s24, s2, 3
	s_lshr_b32 s16, s16, 6
	s_bfe_u32 s27, s2, 0x40002
	s_lshr_b32 s17, s16, 1
	s_lshr_b32 s25, s16, 2
	s_mov_b32 m0, s25
	s_xor_b32 s25, s25, s16
	s_and_b32 s25, s25, 1
	s_lshl_b32 s25, s25, 6
	s_lshl_b32 s26, s24, 2
	s_add_i32 s26, s26, s17
	s_and_b32 s28, s2, -4
	s_lshl_b32 s28, s28, 5
	s_lshl_b32 s29, s27, 7
	s_add_i32 s28, s28, s25
	s_add_i32 s29, s29, s25
	s_lshl_b32 s4, s26, 7
	v_add_u32_e32 v166, s28, v43
	v_mul_u32_u24_e32 v46, 0x3c00, v166
	v_lshl_add_u32 v46, v44, 4, v46
	v_add_u32_e32 v46, s4, v46
	v_lshlrev_b32_e32 v48, 11, v166
	v_lshl_add_u32 v48, v44, 3, v48
	v_add_u32_e32 v48, s4, v48
	v_add_u32_e32 v166, s29, v43
	v_lshlrev_b32_e32 v47, 7, v166
	v_lshl_add_u32 v47, v44, 5, v47
	v_mul_u32_u24_e32 v45, 0x90, v43
	v_lshl_add_u32 v45, v44, 4, v45
	v_mul_u32_u24_e32 v166, 0x210, v43
	v_lshl_add_u32 v166, v44, 3, v166
	v_add_u32_e32 v194, 0x9000, v166
	v_add_u32_e32 v195, 0xb100, v166
	v_add_u32_e32 v196, 0xd200, v166
	v_add_u32_e32 v197, 0xf300, v166
	v_lshlrev_b32_e32 v166, 2, v44
	v_sub_u32_e32 v166, v43, v166
	v_cmp_gt_i32_e64 s[40:41], 0, v166
	v_cmp_gt_i32_e64 s[42:43], 1, v166
	v_cmp_gt_i32_e64 s[44:45], 2, v166
	v_cmp_gt_i32_e64 s[46:47], 3, v166
	v_mov_b32_e32 v49, 0xf149f2ca
	v_lshlrev_b32_e32 v167, 5, v44
	v_mov_b32_e32 v166, s26
	v_lshlrev_b32_e32 v166, 2, v166
	s_mov_b32 s4, s25
	s_mov_b32 vcc_lo, s63
	s_mov_b32 vcc_hi, s78
	s_cmp_lg_u32 s27, 0
	s_cselect_b64 s[28:29], -1, 0
	s_and_b64 s[48:49], s[40:41], s[28:29]
	s_and_b64 s[50:51], s[42:43], s[28:29]
	s_and_b64 s[52:53], s[44:45], s[28:29]
	s_and_b64 s[26:27], s[46:47], s[28:29]
	v_readlane_b32 s6, v250, 36
	v_readlane_b32 s7, v250, 37
	v_readlane_b32 s16, v250, 38
	v_readlane_b32 s17, v250, 39
	v_readlane_b32 s24, v248, 54
	v_readlane_b32 s25, v248, 55
	global_load_dwordx4 v[26:29], v167, s[38:39]
	global_load_dwordx4 v[30:33], v167, s[38:39] offset:16
	global_load_dwordx4 v[34:37], v167, s[38:39] offset:128
	global_load_dwordx4 v[38:41], v167, s[38:39] offset:144
	global_load_dword v42, v166, vcc
	s_nop 1
	global_load_dwordx4 v[2:5], v46, s[10:11]
	global_load_dwordx4 v[6:9], v46, s[10:11] offset:64
	global_load_dwordx4 v[10:13], v47, s[6:7]
	global_load_dwordx4 v[14:17], v47, s[6:7] offset:16
	global_load_dwordx4 v[18:21], v47, s[16:17]
	global_load_dwordx4 v[22:25], v47, s[16:17] offset:16
	v_add_u32_e32 v46, 0x3c000, v46
	v_add_u32_e32 v47, 0x800, v47
	global_load_dwordx4 v[218:221], v46, s[10:11]
	global_load_dwordx4 v[222:225], v46, s[10:11] offset:64
	global_load_dwordx4 v[226:229], v47, s[6:7]
	global_load_dwordx4 v[230:233], v47, s[6:7] offset:16
	global_load_dwordx4 v[234:237], v47, s[16:17]
	global_load_dwordx4 v[238:241], v47, s[16:17] offset:16
	v_add_u32_e32 v46, 0x3c000, v46
	v_add_u32_e32 v47, 0x800, v47
	s_waitcnt lgkmcnt(0)
	s_barrier
	s_cmp_eq_u32 m0, 0
	s_cbranch_scc1 .Latt_nostagger
	s_sleep 16
.Latt_nostagger:
	s_cmp_eq_u32 s4, 0
	s_cbranch_scc1 .Latt_r0
